# SwiGLU epilogues (FFN1 and both FFN2 gate/up): the eight per-row-block ssq loads issued up front with counted waits instead of one load + vmcnt(0) per block
# baseline (speedup 1.0000x reference)
.LBB0_236:
	v_lshl_add_u32 v140, s94, 8, v162
	v_ashrrev_i32_e32 v141, 31, v140
	v_lshl_add_u64 v[142:143], v[140:141], 2, s[8:9]
	global_load_dword v141, v[142:143], off
	global_load_dword v212, v[142:143], off offset:64
	global_load_dword v213, v[142:143], off offset:128
	global_load_dword v214, v[142:143], off offset:192
	global_load_dword v215, v[142:143], off offset:512
	global_load_dword v216, v[142:143], off offset:576
	global_load_dword v217, v[142:143], off offset:640
	global_load_dword v218, v[142:143], off offset:704
	v_lshl_or_b32 v144, s57, 7, v165
	v_ashrrev_i32_e32 v145, 31, v144
	s_mov_b64 s[94:95], -1
	s_waitcnt vmcnt(7)
	v_fmamk_f32 v141, v141, 0x3a800000, v174
	v_cmp_gt_f32_e32 vcc, s89, v141
	v_mul_f32_e32 v175, 0x4b800000, v141
	s_nop 0
	v_cndmask_b32_e32 v141, v141, v175, vcc
	v_rsq_f32_e32 v141, v141
	s_nop 0
	v_mul_f32_e32 v175, 0x45800000, v141
	v_cndmask_b32_e32 v176, v141, v175, vcc
	v_pk_mul_f32 v[126:127], v[126:127], v[176:177] op_sel_hi:[1,0]
	v_pk_mul_f32 v[118:119], v[118:119], v[176:177] op_sel_hi:[1,0]
	v_mul_f32_e32 v141, 0xbfb8aa3b, v126
	v_exp_f32_e32 v141, v141
	v_pk_mul_f32 v[120:121], v[120:121], v[176:177] op_sel_hi:[1,0]
	v_pk_mul_f32 v[122:123], v[122:123], v[176:177] op_sel_hi:[1,0]
	v_pk_mul_f32 v[114:115], v[114:115], v[176:177] op_sel_hi:[1,0]
	v_add_f32_e32 v141, 1.0, v141
	v_rcp_f32_e32 v180, v141
	v_mul_f32_e32 v141, 0xbfb8aa3b, v127
	v_exp_f32_e32 v141, v141
	v_pk_mul_f32 v[116:117], v[116:117], v[176:177] op_sel_hi:[1,0]
	v_add_f32_e32 v141, 1.0, v141
	v_rcp_f32_e32 v181, v141
	s_nop 0
	v_pk_mul_f32 v[126:127], v[126:127], v[180:181]
	s_nop 0
	v_pk_mul_f32 v[118:119], v[118:119], v[126:127]
	v_pk_mul_f32 v[126:127], v[128:129], v[176:177] op_sel_hi:[1,0]
	s_nop 0
	v_mul_f32_e32 v128, 0xbfb8aa3b, v126
	v_mul_f32_e32 v129, 0xbfb8aa3b, v127
	v_exp_f32_e32 v128, v128
	v_exp_f32_e32 v129, v129
	v_add_f32_e32 v128, 1.0, v128
	v_add_f32_e32 v129, 1.0, v129
	v_rcp_f32_e32 v128, v128
	v_rcp_f32_e32 v129, v129
	s_nop 0
	v_pk_mul_f32 v[126:127], v[126:127], v[128:129]
	s_nop 0
	v_pk_mul_f32 v[120:121], v[120:121], v[126:127]
	v_mul_f32_e32 v126, 0xbfb8aa3b, v122
	v_mul_f32_e32 v127, 0xbfb8aa3b, v123
	v_exp_f32_e32 v126, v126
	v_exp_f32_e32 v127, v127
	v_add_f32_e32 v126, 1.0, v126
	v_add_f32_e32 v127, 1.0, v127
	v_rcp_f32_e32 v126, v126
	v_rcp_f32_e32 v127, v127
	s_nop 0
	v_pk_mul_f32 v[122:123], v[122:123], v[126:127]
	s_nop 0
	v_pk_mul_f32 v[122:123], v[114:115], v[122:123]
	v_pk_mul_f32 v[114:115], v[124:125], v[176:177] op_sel_hi:[1,0]
	s_nop 0
	v_mul_f32_e32 v124, 0xbfb8aa3b, v114
	v_mul_f32_e32 v125, 0xbfb8aa3b, v115
	v_exp_f32_e32 v124, v124
	v_exp_f32_e32 v125, v125
	v_add_f32_e32 v124, 1.0, v124
	v_add_f32_e32 v125, 1.0, v125
	v_rcp_f32_e32 v124, v124
	v_rcp_f32_e32 v125, v125
	s_nop 0
	v_pk_mul_f32 v[114:115], v[114:115], v[124:125]
	s_nop 0
	v_pk_mul_f32 v[124:125], v[116:117], v[114:115]
	v_cvt_pk_bf16_f32 v114, v118, v119
	v_mov_b64_e32 v[118:119], s[38:39]
	v_cvt_pk_bf16_f32 v115, v120, v121
	v_cvt_pk_bf16_f32 v116, v122, v123
	v_mad_i64_i32 v[122:123], s[6:7], v140, s56, v[118:119]
	v_lshlrev_b64 v[120:121], 1, v[144:145]
	v_cvt_pk_bf16_f32 v117, v124, v125
	v_lshl_add_u64 v[122:123], v[122:123], 0, v[120:121]
	global_store_dwordx4 v[122:123], v[114:117], off
	s_nop 0
	s_waitcnt vmcnt(7)
	v_mov_b32_e32 v114, v212
	v_fmamk_f32 v114, v114, 0x3a800000, v174
	v_cmp_gt_f32_e32 vcc, s89, v114
	v_mul_f32_e32 v115, 0x4b800000, v114
	s_nop 0
	v_cndmask_b32_e32 v114, v114, v115, vcc
	v_rsq_f32_e32 v114, v114
	s_nop 0
	v_mul_f32_e32 v115, 0x45800000, v114
	v_cndmask_b32_e32 v114, v114, v115, vcc
	v_pk_mul_f32 v[110:111], v[110:111], v[114:115] op_sel_hi:[1,0]
	s_nop 0
	v_mul_f32_e32 v115, 0xbfb8aa3b, v110
	v_exp_f32_e32 v115, v115
	s_nop 0
	v_add_f32_e32 v115, 1.0, v115
	v_rcp_f32_e32 v116, v115
	v_pk_mul_f32 v[102:103], v[102:103], v[114:115] op_sel_hi:[1,0]
	v_mul_f32_e32 v115, 0xbfb8aa3b, v111
	v_exp_f32_e32 v115, v115
	s_nop 0
	v_add_f32_e32 v115, 1.0, v115
	v_rcp_f32_e32 v117, v115
	v_pk_mul_f32 v[104:105], v[104:105], v[114:115] op_sel_hi:[1,0]
	v_pk_mul_f32 v[106:107], v[106:107], v[114:115] op_sel_hi:[1,0]
	v_pk_mul_f32 v[98:99], v[98:99], v[114:115] op_sel_hi:[1,0]
	v_pk_mul_f32 v[110:111], v[110:111], v[116:117]
	v_pk_mul_f32 v[100:101], v[100:101], v[114:115] op_sel_hi:[1,0]
	v_pk_mul_f32 v[102:103], v[102:103], v[110:111]
	v_pk_mul_f32 v[110:111], v[112:113], v[114:115] op_sel_hi:[1,0]
	s_nop 0
	v_mul_f32_e32 v112, 0xbfb8aa3b, v110
	v_mul_f32_e32 v113, 0xbfb8aa3b, v111
	v_exp_f32_e32 v112, v112
	v_exp_f32_e32 v113, v113
	v_add_f32_e32 v112, 1.0, v112
	v_add_f32_e32 v113, 1.0, v113
	v_rcp_f32_e32 v112, v112
	v_rcp_f32_e32 v113, v113
	s_nop 0
	v_pk_mul_f32 v[110:111], v[110:111], v[112:113]
	s_nop 0
	v_pk_mul_f32 v[104:105], v[104:105], v[110:111]
	v_mul_f32_e32 v110, 0xbfb8aa3b, v106
	v_mul_f32_e32 v111, 0xbfb8aa3b, v107
	v_exp_f32_e32 v110, v110
	v_exp_f32_e32 v111, v111
	v_add_f32_e32 v110, 1.0, v110
	v_add_f32_e32 v111, 1.0, v111
	v_rcp_f32_e32 v110, v110
	v_rcp_f32_e32 v111, v111
	s_nop 0
	v_pk_mul_f32 v[106:107], v[106:107], v[110:111]
	s_nop 0
	v_pk_mul_f32 v[106:107], v[98:99], v[106:107]
	v_pk_mul_f32 v[98:99], v[108:109], v[114:115] op_sel_hi:[1,0]
	v_or_b32_e32 v110, 16, v140
	v_mul_f32_e32 v108, 0xbfb8aa3b, v98
	v_mul_f32_e32 v109, 0xbfb8aa3b, v99
	v_exp_f32_e32 v108, v108
	v_exp_f32_e32 v109, v109
	v_add_f32_e32 v108, 1.0, v108
	v_add_f32_e32 v109, 1.0, v109
	v_rcp_f32_e32 v108, v108
	v_rcp_f32_e32 v109, v109
	s_nop 0
	v_pk_mul_f32 v[98:99], v[98:99], v[108:109]
	s_nop 0
	v_pk_mul_f32 v[108:109], v[100:101], v[98:99]
	v_cvt_pk_bf16_f32 v98, v102, v103
	v_mad_i64_i32 v[102:103], s[6:7], v110, s56, v[118:119]
	v_cvt_pk_bf16_f32 v99, v104, v105
	v_cvt_pk_bf16_f32 v100, v106, v107
	v_cvt_pk_bf16_f32 v101, v108, v109
	v_lshl_add_u64 v[102:103], v[102:103], 0, v[120:121]
	global_store_dwordx4 v[102:103], v[98:101], off
	s_nop 0
	s_waitcnt vmcnt(7)
	v_mov_b32_e32 v98, v213
	v_fmamk_f32 v98, v98, 0x3a800000, v174
	v_cmp_gt_f32_e32 vcc, s89, v98
	v_mul_f32_e32 v99, 0x4b800000, v98
	s_nop 0
	v_cndmask_b32_e32 v98, v98, v99, vcc
	v_rsq_f32_e32 v98, v98
	s_nop 0
	v_mul_f32_e32 v99, 0x45800000, v98
	v_cndmask_b32_e32 v98, v98, v99, vcc
	v_pk_mul_f32 v[94:95], v[94:95], v[98:99] op_sel_hi:[1,0]
	s_nop 0
	v_mul_f32_e32 v99, 0xbfb8aa3b, v94
	v_exp_f32_e32 v99, v99
	s_nop 0
	v_add_f32_e32 v99, 1.0, v99
	v_rcp_f32_e32 v100, v99
	v_pk_mul_f32 v[86:87], v[86:87], v[98:99] op_sel_hi:[1,0]
	v_mul_f32_e32 v99, 0xbfb8aa3b, v95
	v_exp_f32_e32 v99, v99
	s_nop 0
	v_add_f32_e32 v99, 1.0, v99
	v_rcp_f32_e32 v101, v99
	v_pk_mul_f32 v[88:89], v[88:89], v[98:99] op_sel_hi:[1,0]
	v_pk_mul_f32 v[90:91], v[90:91], v[98:99] op_sel_hi:[1,0]
	v_pk_mul_f32 v[82:83], v[82:83], v[98:99] op_sel_hi:[1,0]
	v_pk_mul_f32 v[94:95], v[94:95], v[100:101]
	v_pk_mul_f32 v[84:85], v[84:85], v[98:99] op_sel_hi:[1,0]
	v_pk_mul_f32 v[86:87], v[86:87], v[94:95]
	v_pk_mul_f32 v[94:95], v[96:97], v[98:99] op_sel_hi:[1,0]
	s_nop 0
	v_mul_f32_e32 v96, 0xbfb8aa3b, v94
	v_mul_f32_e32 v97, 0xbfb8aa3b, v95
	v_exp_f32_e32 v96, v96
	v_exp_f32_e32 v97, v97
	v_add_f32_e32 v96, 1.0, v96
	v_add_f32_e32 v97, 1.0, v97
	v_rcp_f32_e32 v96, v96
	v_rcp_f32_e32 v97, v97
	s_nop 0
	v_pk_mul_f32 v[94:95], v[94:95], v[96:97]
	s_nop 0
	v_pk_mul_f32 v[88:89], v[88:89], v[94:95]
	v_mul_f32_e32 v94, 0xbfb8aa3b, v90
	v_mul_f32_e32 v95, 0xbfb8aa3b, v91
	v_exp_f32_e32 v94, v94
	v_exp_f32_e32 v95, v95
	v_add_f32_e32 v94, 1.0, v94
	v_add_f32_e32 v95, 1.0, v95
	v_rcp_f32_e32 v94, v94
	v_rcp_f32_e32 v95, v95
	s_nop 0
	v_pk_mul_f32 v[90:91], v[90:91], v[94:95]
	s_nop 0
	v_pk_mul_f32 v[90:91], v[82:83], v[90:91]
	v_pk_mul_f32 v[82:83], v[92:93], v[98:99] op_sel_hi:[1,0]
	v_or_b32_e32 v94, 32, v140
	v_mul_f32_e32 v92, 0xbfb8aa3b, v82
	v_mul_f32_e32 v93, 0xbfb8aa3b, v83
	v_exp_f32_e32 v92, v92
	v_exp_f32_e32 v93, v93
	v_add_f32_e32 v92, 1.0, v92
	v_add_f32_e32 v93, 1.0, v93
	v_rcp_f32_e32 v92, v92
	v_rcp_f32_e32 v93, v93
	s_nop 0
	v_pk_mul_f32 v[82:83], v[82:83], v[92:93]
	s_nop 0
	v_pk_mul_f32 v[92:93], v[84:85], v[82:83]
	v_cvt_pk_bf16_f32 v82, v86, v87
	v_mad_i64_i32 v[86:87], s[6:7], v94, s56, v[118:119]
	v_cvt_pk_bf16_f32 v83, v88, v89
	v_cvt_pk_bf16_f32 v84, v90, v91
	v_cvt_pk_bf16_f32 v85, v92, v93
	v_lshl_add_u64 v[86:87], v[86:87], 0, v[120:121]
	global_store_dwordx4 v[86:87], v[82:85], off
	s_nop 0
	s_waitcnt vmcnt(7)
	v_mov_b32_e32 v82, v214
	v_fmamk_f32 v82, v82, 0x3a800000, v174
	v_cmp_gt_f32_e32 vcc, s89, v82
	v_mul_f32_e32 v83, 0x4b800000, v82
	s_nop 0
	v_cndmask_b32_e32 v82, v82, v83, vcc
	v_rsq_f32_e32 v82, v82
	s_nop 0
	v_mul_f32_e32 v83, 0x45800000, v82
	v_cndmask_b32_e32 v82, v82, v83, vcc
	v_pk_mul_f32 v[78:79], v[78:79], v[82:83] op_sel_hi:[1,0]
	s_nop 0
	v_mul_f32_e32 v83, 0xbfb8aa3b, v78
	v_exp_f32_e32 v83, v83
	s_nop 0
	v_add_f32_e32 v83, 1.0, v83
	v_rcp_f32_e32 v84, v83
	v_pk_mul_f32 v[70:71], v[70:71], v[82:83] op_sel_hi:[1,0]
	v_mul_f32_e32 v83, 0xbfb8aa3b, v79
	v_exp_f32_e32 v83, v83
	s_nop 0
	v_add_f32_e32 v83, 1.0, v83
	v_rcp_f32_e32 v85, v83
	v_pk_mul_f32 v[72:73], v[72:73], v[82:83] op_sel_hi:[1,0]
	v_pk_mul_f32 v[74:75], v[74:75], v[82:83] op_sel_hi:[1,0]
	v_pk_mul_f32 v[66:67], v[66:67], v[82:83] op_sel_hi:[1,0]
	v_pk_mul_f32 v[78:79], v[78:79], v[84:85]
	v_pk_mul_f32 v[68:69], v[68:69], v[82:83] op_sel_hi:[1,0]
	v_pk_mul_f32 v[70:71], v[70:71], v[78:79]
	v_pk_mul_f32 v[78:79], v[80:81], v[82:83] op_sel_hi:[1,0]
	s_nop 0
	v_mul_f32_e32 v80, 0xbfb8aa3b, v78
	v_mul_f32_e32 v81, 0xbfb8aa3b, v79
	v_exp_f32_e32 v80, v80
	v_exp_f32_e32 v81, v81
	v_add_f32_e32 v80, 1.0, v80
	v_add_f32_e32 v81, 1.0, v81
	v_rcp_f32_e32 v80, v80
	v_rcp_f32_e32 v81, v81
	s_nop 0
	v_pk_mul_f32 v[78:79], v[78:79], v[80:81]
	s_nop 0
	v_pk_mul_f32 v[72:73], v[72:73], v[78:79]
	v_mul_f32_e32 v78, 0xbfb8aa3b, v74
	v_mul_f32_e32 v79, 0xbfb8aa3b, v75
	v_exp_f32_e32 v78, v78
	v_exp_f32_e32 v79, v79
	v_add_f32_e32 v78, 1.0, v78
	v_add_f32_e32 v79, 1.0, v79
	v_rcp_f32_e32 v78, v78
	v_rcp_f32_e32 v79, v79
	s_nop 0
	v_pk_mul_f32 v[74:75], v[74:75], v[78:79]
	s_nop 0
	v_pk_mul_f32 v[74:75], v[66:67], v[74:75]
	v_pk_mul_f32 v[66:67], v[76:77], v[82:83] op_sel_hi:[1,0]
	v_or_b32_e32 v78, 48, v140
	v_mul_f32_e32 v76, 0xbfb8aa3b, v66
	v_mul_f32_e32 v77, 0xbfb8aa3b, v67
	v_exp_f32_e32 v76, v76
	v_exp_f32_e32 v77, v77
	v_add_f32_e32 v76, 1.0, v76
	v_add_f32_e32 v77, 1.0, v77
	v_rcp_f32_e32 v76, v76
	v_rcp_f32_e32 v77, v77
	s_nop 0
	v_pk_mul_f32 v[66:67], v[66:67], v[76:77]
	s_nop 0
	v_pk_mul_f32 v[76:77], v[68:69], v[66:67]
	v_cvt_pk_bf16_f32 v66, v70, v71
	v_mad_i64_i32 v[70:71], s[6:7], v78, s56, v[118:119]
	v_cvt_pk_bf16_f32 v67, v72, v73
	v_cvt_pk_bf16_f32 v68, v74, v75
	v_cvt_pk_bf16_f32 v69, v76, v77
	v_lshl_add_u64 v[70:71], v[70:71], 0, v[120:121]
	global_store_dwordx4 v[70:71], v[66:69], off
	s_nop 0
	s_nop 0
	v_add_u32_e32 v67, 0x80, v140
	s_waitcnt vmcnt(7)
	v_mov_b32_e32 v66, v215
	v_fmamk_f32 v66, v66, 0x3a800000, v174
	v_cmp_gt_f32_e32 vcc, s89, v66
	v_mul_f32_e32 v68, 0x4b800000, v66
	s_nop 0
	v_cndmask_b32_e32 v66, v66, v68, vcc
	v_rsq_f32_e32 v66, v66
	s_nop 0
	v_mul_f32_e32 v68, 0x45800000, v66
	v_cndmask_b32_e32 v66, v66, v68, vcc
	v_pk_mul_f32 v[62:63], v[62:63], v[66:67] op_sel_hi:[1,0]
	v_pk_mul_f32 v[54:55], v[54:55], v[66:67] op_sel_hi:[1,0]
	v_mul_f32_e32 v68, 0xbfb8aa3b, v62
	v_mul_f32_e32 v69, 0xbfb8aa3b, v63
	v_exp_f32_e32 v68, v68
	v_exp_f32_e32 v69, v69
	v_pk_mul_f32 v[56:57], v[56:57], v[66:67] op_sel_hi:[1,0]
	v_pk_mul_f32 v[58:59], v[58:59], v[66:67] op_sel_hi:[1,0]
	v_add_f32_e32 v68, 1.0, v68
	v_add_f32_e32 v69, 1.0, v69
	v_rcp_f32_e32 v68, v68
	v_rcp_f32_e32 v69, v69
	v_pk_mul_f32 v[50:51], v[50:51], v[66:67] op_sel_hi:[1,0]
	v_pk_mul_f32 v[52:53], v[52:53], v[66:67] op_sel_hi:[1,0]
	v_pk_mul_f32 v[62:63], v[62:63], v[68:69]
	s_nop 0
	v_pk_mul_f32 v[54:55], v[54:55], v[62:63]
	v_pk_mul_f32 v[62:63], v[64:65], v[66:67] op_sel_hi:[1,0]
	s_nop 0
	v_mul_f32_e32 v64, 0xbfb8aa3b, v62
	v_mul_f32_e32 v65, 0xbfb8aa3b, v63
	v_exp_f32_e32 v64, v64
	v_exp_f32_e32 v65, v65
	v_add_f32_e32 v64, 1.0, v64
	v_add_f32_e32 v65, 1.0, v65
	v_rcp_f32_e32 v64, v64
	v_rcp_f32_e32 v65, v65
	s_nop 0
	v_pk_mul_f32 v[62:63], v[62:63], v[64:65]
	s_nop 0
	v_pk_mul_f32 v[56:57], v[56:57], v[62:63]
	v_mul_f32_e32 v62, 0xbfb8aa3b, v58
	v_mul_f32_e32 v63, 0xbfb8aa3b, v59
	v_exp_f32_e32 v62, v62
	v_exp_f32_e32 v63, v63
	v_add_f32_e32 v62, 1.0, v62
	v_add_f32_e32 v63, 1.0, v63
	v_rcp_f32_e32 v62, v62
	v_rcp_f32_e32 v63, v63
	s_nop 0
	v_pk_mul_f32 v[58:59], v[58:59], v[62:63]
	s_nop 0
	v_pk_mul_f32 v[58:59], v[50:51], v[58:59]
	v_pk_mul_f32 v[50:51], v[60:61], v[66:67] op_sel_hi:[1,0]
	s_nop 0
	v_mul_f32_e32 v60, 0xbfb8aa3b, v50
	v_mul_f32_e32 v61, 0xbfb8aa3b, v51
	v_exp_f32_e32 v60, v60
	v_exp_f32_e32 v61, v61
	v_add_f32_e32 v60, 1.0, v60
	v_add_f32_e32 v61, 1.0, v61
	v_rcp_f32_e32 v60, v60
	v_rcp_f32_e32 v61, v61
	s_nop 0
	v_pk_mul_f32 v[50:51], v[50:51], v[60:61]
	s_nop 0
	v_pk_mul_f32 v[60:61], v[52:53], v[50:51]
	v_cvt_pk_bf16_f32 v50, v54, v55
	v_mad_i64_i32 v[54:55], s[6:7], v67, s56, v[118:119]
	v_cvt_pk_bf16_f32 v51, v56, v57
	v_cvt_pk_bf16_f32 v52, v58, v59
	v_cvt_pk_bf16_f32 v53, v60, v61
	v_lshl_add_u64 v[54:55], v[54:55], 0, v[120:121]
	global_store_dwordx4 v[54:55], v[50:53], off
	s_nop 0
	s_waitcnt vmcnt(7)
	v_mov_b32_e32 v50, v216
	v_fmamk_f32 v50, v50, 0x3a800000, v174
	v_cmp_gt_f32_e32 vcc, s89, v50
	v_mul_f32_e32 v51, 0x4b800000, v50
	s_nop 0
	v_cndmask_b32_e32 v50, v50, v51, vcc
	v_rsq_f32_e32 v50, v50
	s_nop 0
	v_mul_f32_e32 v51, 0x45800000, v50
	v_cndmask_b32_e32 v50, v50, v51, vcc
	v_pk_mul_f32 v[46:47], v[46:47], v[50:51] op_sel_hi:[1,0]
	s_nop 0
	v_mul_f32_e32 v51, 0xbfb8aa3b, v46
	v_exp_f32_e32 v51, v51
	s_nop 0
	v_add_f32_e32 v51, 1.0, v51
	v_rcp_f32_e32 v52, v51
	v_pk_mul_f32 v[38:39], v[38:39], v[50:51] op_sel_hi:[1,0]
	v_mul_f32_e32 v51, 0xbfb8aa3b, v47
	v_exp_f32_e32 v51, v51
	s_nop 0
	v_add_f32_e32 v51, 1.0, v51
	v_rcp_f32_e32 v53, v51
	v_pk_mul_f32 v[40:41], v[40:41], v[50:51] op_sel_hi:[1,0]
	v_pk_mul_f32 v[42:43], v[42:43], v[50:51] op_sel_hi:[1,0]
	v_pk_mul_f32 v[34:35], v[34:35], v[50:51] op_sel_hi:[1,0]
	v_pk_mul_f32 v[46:47], v[46:47], v[52:53]
	v_pk_mul_f32 v[36:37], v[36:37], v[50:51] op_sel_hi:[1,0]
	v_pk_mul_f32 v[38:39], v[38:39], v[46:47]
	v_pk_mul_f32 v[46:47], v[48:49], v[50:51] op_sel_hi:[1,0]
	s_nop 0
	v_mul_f32_e32 v48, 0xbfb8aa3b, v46
	v_mul_f32_e32 v49, 0xbfb8aa3b, v47
	v_exp_f32_e32 v48, v48
	v_exp_f32_e32 v49, v49
	v_add_f32_e32 v48, 1.0, v48
	v_add_f32_e32 v49, 1.0, v49
	v_rcp_f32_e32 v48, v48
	v_rcp_f32_e32 v49, v49
	s_nop 0
	v_pk_mul_f32 v[46:47], v[46:47], v[48:49]
	s_nop 0
	v_pk_mul_f32 v[40:41], v[40:41], v[46:47]
	v_mul_f32_e32 v46, 0xbfb8aa3b, v42
	v_mul_f32_e32 v47, 0xbfb8aa3b, v43
	v_exp_f32_e32 v46, v46
	v_exp_f32_e32 v47, v47
	v_add_f32_e32 v46, 1.0, v46
	v_add_f32_e32 v47, 1.0, v47
	v_rcp_f32_e32 v46, v46
	v_rcp_f32_e32 v47, v47
	s_nop 0
	v_pk_mul_f32 v[42:43], v[42:43], v[46:47]
	s_nop 0
	v_pk_mul_f32 v[42:43], v[34:35], v[42:43]
	v_pk_mul_f32 v[34:35], v[44:45], v[50:51] op_sel_hi:[1,0]
	v_add_u32_e32 v46, 0x90, v140
	v_mul_f32_e32 v44, 0xbfb8aa3b, v34
	v_mul_f32_e32 v45, 0xbfb8aa3b, v35
	v_exp_f32_e32 v44, v44
	v_exp_f32_e32 v45, v45
	v_add_f32_e32 v44, 1.0, v44
	v_add_f32_e32 v45, 1.0, v45
	v_rcp_f32_e32 v44, v44
	v_rcp_f32_e32 v45, v45
	s_nop 0
	v_pk_mul_f32 v[34:35], v[34:35], v[44:45]
	s_nop 0
	v_pk_mul_f32 v[44:45], v[36:37], v[34:35]
	v_cvt_pk_bf16_f32 v34, v38, v39
	v_mad_i64_i32 v[38:39], s[6:7], v46, s56, v[118:119]
	v_cvt_pk_bf16_f32 v35, v40, v41
	v_cvt_pk_bf16_f32 v36, v42, v43
	v_cvt_pk_bf16_f32 v37, v44, v45
	v_lshl_add_u64 v[38:39], v[38:39], 0, v[120:121]
	global_store_dwordx4 v[38:39], v[34:37], off
	s_nop 0
	s_waitcnt vmcnt(7)
	v_mov_b32_e32 v34, v217
	v_fmamk_f32 v34, v34, 0x3a800000, v174
	v_cmp_gt_f32_e32 vcc, s89, v34
	v_mul_f32_e32 v35, 0x4b800000, v34
	s_nop 0
	v_cndmask_b32_e32 v34, v34, v35, vcc
	v_rsq_f32_e32 v34, v34
	s_nop 0
	v_mul_f32_e32 v35, 0x45800000, v34
	v_cndmask_b32_e32 v34, v34, v35, vcc
	v_pk_mul_f32 v[30:31], v[30:31], v[34:35] op_sel_hi:[1,0]
	s_nop 0
	v_mul_f32_e32 v35, 0xbfb8aa3b, v30
	v_exp_f32_e32 v35, v35
	s_nop 0
	v_add_f32_e32 v35, 1.0, v35
	v_rcp_f32_e32 v36, v35
	v_pk_mul_f32 v[22:23], v[22:23], v[34:35] op_sel_hi:[1,0]
	v_mul_f32_e32 v35, 0xbfb8aa3b, v31
	v_exp_f32_e32 v35, v35
	s_nop 0
	v_add_f32_e32 v35, 1.0, v35
	v_rcp_f32_e32 v37, v35
	v_pk_mul_f32 v[24:25], v[24:25], v[34:35] op_sel_hi:[1,0]
	v_pk_mul_f32 v[26:27], v[26:27], v[34:35] op_sel_hi:[1,0]
	v_pk_mul_f32 v[18:19], v[18:19], v[34:35] op_sel_hi:[1,0]
	v_pk_mul_f32 v[30:31], v[30:31], v[36:37]
	v_pk_mul_f32 v[20:21], v[20:21], v[34:35] op_sel_hi:[1,0]
	v_pk_mul_f32 v[22:23], v[22:23], v[30:31]
	v_pk_mul_f32 v[30:31], v[32:33], v[34:35] op_sel_hi:[1,0]
	s_nop 0
	v_mul_f32_e32 v32, 0xbfb8aa3b, v30
	v_mul_f32_e32 v33, 0xbfb8aa3b, v31
	v_exp_f32_e32 v32, v32
	v_exp_f32_e32 v33, v33
	v_add_f32_e32 v32, 1.0, v32
	v_add_f32_e32 v33, 1.0, v33
	v_rcp_f32_e32 v32, v32
	v_rcp_f32_e32 v33, v33
	s_nop 0
	v_pk_mul_f32 v[30:31], v[30:31], v[32:33]
	s_nop 0
	v_pk_mul_f32 v[24:25], v[24:25], v[30:31]
	v_mul_f32_e32 v30, 0xbfb8aa3b, v26
	v_mul_f32_e32 v31, 0xbfb8aa3b, v27
	v_exp_f32_e32 v30, v30
	v_exp_f32_e32 v31, v31
	v_add_f32_e32 v30, 1.0, v30
	v_add_f32_e32 v31, 1.0, v31
	v_rcp_f32_e32 v30, v30
	v_rcp_f32_e32 v31, v31
	s_nop 0
	v_pk_mul_f32 v[26:27], v[26:27], v[30:31]
	s_nop 0
	v_pk_mul_f32 v[26:27], v[18:19], v[26:27]
	v_pk_mul_f32 v[18:19], v[28:29], v[34:35] op_sel_hi:[1,0]
	v_add_u32_e32 v30, 0xa0, v140
	v_mul_f32_e32 v28, 0xbfb8aa3b, v18
	v_mul_f32_e32 v29, 0xbfb8aa3b, v19
	v_exp_f32_e32 v28, v28
	v_exp_f32_e32 v29, v29
	v_add_f32_e32 v28, 1.0, v28
	v_add_f32_e32 v29, 1.0, v29
	v_rcp_f32_e32 v28, v28
	v_rcp_f32_e32 v29, v29
	s_nop 0
	v_pk_mul_f32 v[18:19], v[18:19], v[28:29]
	s_nop 0
	v_pk_mul_f32 v[28:29], v[20:21], v[18:19]
	v_cvt_pk_bf16_f32 v18, v22, v23
	v_mad_i64_i32 v[22:23], s[6:7], v30, s56, v[118:119]
	v_cvt_pk_bf16_f32 v19, v24, v25
	v_cvt_pk_bf16_f32 v20, v26, v27
	v_cvt_pk_bf16_f32 v21, v28, v29
	v_lshl_add_u64 v[22:23], v[22:23], 0, v[120:121]
	global_store_dwordx4 v[22:23], v[18:21], off
	s_nop 0
	s_waitcnt vmcnt(7)
	v_mov_b32_e32 v18, v218
	v_fmamk_f32 v18, v18, 0x3a800000, v174
	v_cmp_gt_f32_e32 vcc, s89, v18
	v_mul_f32_e32 v19, 0x4b800000, v18
	s_nop 0
	v_cndmask_b32_e32 v18, v18, v19, vcc
	v_rsq_f32_e32 v18, v18
	s_nop 0
	v_mul_f32_e32 v19, 0x45800000, v18
	v_cndmask_b32_e32 v18, v18, v19, vcc
	v_pk_mul_f32 v[14:15], v[14:15], v[18:19] op_sel_hi:[1,0]
	s_andn2_b64 vcc, exec, s[0:1]
	v_mul_f32_e32 v19, 0xbfb8aa3b, v14
	v_exp_f32_e32 v19, v19
	s_nop 0
	v_add_f32_e32 v19, 1.0, v19
	v_rcp_f32_e32 v20, v19
	v_pk_mul_f32 v[6:7], v[6:7], v[18:19] op_sel_hi:[1,0]
	v_mul_f32_e32 v19, 0xbfb8aa3b, v15
	v_exp_f32_e32 v19, v19
	s_nop 0
	v_add_f32_e32 v19, 1.0, v19
	v_rcp_f32_e32 v21, v19
	v_pk_mul_f32 v[8:9], v[8:9], v[18:19] op_sel_hi:[1,0]
	v_pk_mul_f32 v[10:11], v[10:11], v[18:19] op_sel_hi:[1,0]
	v_pk_mul_f32 v[2:3], v[2:3], v[18:19] op_sel_hi:[1,0]
	v_pk_mul_f32 v[14:15], v[14:15], v[20:21]
	v_pk_mul_f32 v[4:5], v[4:5], v[18:19] op_sel_hi:[1,0]
	v_pk_mul_f32 v[6:7], v[6:7], v[14:15]
	v_pk_mul_f32 v[14:15], v[16:17], v[18:19] op_sel_hi:[1,0]
	s_nop 0
	v_mul_f32_e32 v16, 0xbfb8aa3b, v14
	v_mul_f32_e32 v17, 0xbfb8aa3b, v15
	v_exp_f32_e32 v16, v16
	v_exp_f32_e32 v17, v17
	v_add_f32_e32 v16, 1.0, v16
	v_add_f32_e32 v17, 1.0, v17
	v_rcp_f32_e32 v16, v16
	v_rcp_f32_e32 v17, v17
	s_nop 0
	v_pk_mul_f32 v[14:15], v[14:15], v[16:17]
	s_nop 0
	v_pk_mul_f32 v[8:9], v[8:9], v[14:15]
	v_mul_f32_e32 v14, 0xbfb8aa3b, v10
	v_mul_f32_e32 v15, 0xbfb8aa3b, v11
	v_exp_f32_e32 v14, v14
	v_exp_f32_e32 v15, v15
	v_add_f32_e32 v14, 1.0, v14
	v_add_f32_e32 v15, 1.0, v15
	v_rcp_f32_e32 v14, v14
	v_rcp_f32_e32 v15, v15
	s_nop 0
	v_pk_mul_f32 v[10:11], v[10:11], v[14:15]
	s_nop 0
	v_pk_mul_f32 v[10:11], v[2:3], v[10:11]
	v_pk_mul_f32 v[2:3], v[12:13], v[18:19] op_sel_hi:[1,0]
	v_add_u32_e32 v14, 0xb0, v140
	v_mul_f32_e32 v12, 0xbfb8aa3b, v2
	v_mul_f32_e32 v13, 0xbfb8aa3b, v3
	v_exp_f32_e32 v12, v12
	v_exp_f32_e32 v13, v13
	v_add_f32_e32 v12, 1.0, v12
	v_add_f32_e32 v13, 1.0, v13
	v_rcp_f32_e32 v12, v12
	v_rcp_f32_e32 v13, v13
	s_nop 0
	v_pk_mul_f32 v[2:3], v[2:3], v[12:13]
	s_nop 0
	v_pk_mul_f32 v[12:13], v[4:5], v[2:3]
	v_cvt_pk_bf16_f32 v2, v6, v7
	v_mad_i64_i32 v[6:7], s[6:7], v14, s56, v[118:119]
	v_cvt_pk_bf16_f32 v3, v8, v9
	v_cvt_pk_bf16_f32 v4, v10, v11
	v_cvt_pk_bf16_f32 v5, v12, v13
	v_lshl_add_u64 v[6:7], v[6:7], 0, v[120:121]
	global_store_dwordx4 v[6:7], v[2:5], off
	s_cbranch_vccnz .LBB0_229
	s_andn2_b64 vcc, exec, s[4:5]
	s_cbranch_vccnz .LBB0_228
	s_barrier
	s_branch .LBB0_228

.LBB0_1527:
	s_lshl_b32 s4, s8, 8
	s_add_i32 s5, s4, 0xb00
	s_cmp_lt_i32 s8, 21
	s_cselect_b32 s5, s4, s5
	v_add_u32_e32 v138, s5, v144
	v_ashrrev_i32_e32 v139, 31, v138
	v_lshl_add_u64 v[142:143], v[138:139], 2, s[56:57]
	global_load_dword v167, v[142:143], off
	global_load_dword v212, v[142:143], off offset:64
	global_load_dword v213, v[142:143], off offset:128
	global_load_dword v214, v[142:143], off offset:192
	global_load_dword v215, v[142:143], off offset:512
	global_load_dword v216, v[142:143], off offset:576
	global_load_dword v217, v[142:143], off offset:640
	global_load_dword v218, v[142:143], off offset:704
	v_readlane_b32 s6, v255, 38
	v_lshl_or_b32 v140, s76, 7, v157
	v_readlane_b32 s7, v255, 39
	v_add_u32_e32 v166, s4, v144
	v_ashrrev_i32_e32 v141, 31, v140
	v_mov_b64_e32 v[138:139], s[6:7]
	v_mad_i64_i32 v[174:175], s[4:5], v166, s75, v[138:139]
	v_lshlrev_b64 v[140:141], 1, v[140:141]
	v_lshl_add_u64 v[174:175], v[174:175], 0, v[140:141]
	s_waitcnt vmcnt(7)
	v_fmamk_f32 v167, v167, 0x3a800000, v165
	v_mul_f32_e32 v168, 0x4b800000, v167
	v_cmp_gt_f32_e32 vcc, s74, v167
	s_nop 1
	v_cndmask_b32_e32 v167, v167, v168, vcc
	v_rsq_f32_e32 v167, v167
	s_nop 0
	v_mul_f32_e32 v168, 0x45800000, v167
	v_cndmask_b32_e32 v168, v167, v168, vcc
	v_pk_mul_f32 v[126:127], v[126:127], v[168:169] op_sel_hi:[1,0]
	v_pk_mul_f32 v[128:129], v[128:129], v[168:169] op_sel_hi:[1,0]
	v_pk_mul_f32 v[122:123], v[122:123], v[168:169] op_sel_hi:[1,0]
	v_pk_mul_f32 v[124:125], v[124:125], v[168:169] op_sel_hi:[1,0]
	v_pk_mul_f32 v[118:119], v[118:119], v[168:169] op_sel_hi:[1,0]
	v_pk_mul_f32 v[120:121], v[120:121], v[168:169] op_sel_hi:[1,0]
	v_pk_mul_f32 v[114:115], v[114:115], v[168:169] op_sel_hi:[1,0]
	v_pk_mul_f32 v[116:117], v[116:117], v[168:169] op_sel_hi:[1,0]
	v_mul_f32_e32 v167, 0xbfb8aa3b, v126
	v_mul_f32_e32 v168, 0xbfb8aa3b, v127
	v_mul_f32_e32 v171, 0xbfb8aa3b, v128
	v_mul_f32_e32 v172, 0xbfb8aa3b, v129
	v_mul_f32_e32 v176, 0xbfb8aa3b, v122
	v_mul_f32_e32 v177, 0xbfb8aa3b, v123
	v_mul_f32_e32 v178, 0xbfb8aa3b, v124
	v_mul_f32_e32 v180, 0xbfb8aa3b, v125
	v_exp_f32_e32 v167, v167
	v_exp_f32_e32 v168, v168
	v_exp_f32_e32 v171, v171
	v_exp_f32_e32 v172, v172
	v_exp_f32_e32 v176, v176
	v_exp_f32_e32 v177, v177
	v_exp_f32_e32 v178, v178
	v_exp_f32_e32 v180, v180
	v_add_f32_e32 v167, 1.0, v167
	v_add_f32_e32 v168, 1.0, v168
	v_add_f32_e32 v171, 1.0, v171
	v_add_f32_e32 v172, 1.0, v172
	v_add_f32_e32 v182, 1.0, v176
	v_add_f32_e32 v183, 1.0, v177
	v_add_f32_e32 v178, 1.0, v178
	v_add_f32_e32 v185, 1.0, v180
	v_rcp_f32_e32 v176, v167
	v_rcp_f32_e32 v177, v168
	v_rcp_f32_e32 v180, v171
	v_rcp_f32_e32 v181, v172
	v_rcp_f32_e32 v182, v182
	v_rcp_f32_e32 v183, v183
	v_rcp_f32_e32 v184, v178
	v_rcp_f32_e32 v185, v185
	v_pk_mul_f32 v[126:127], v[126:127], v[176:177]
	v_pk_mul_f32 v[128:129], v[128:129], v[180:181]
	v_pk_mul_f32 v[122:123], v[122:123], v[182:183]
	v_pk_mul_f32 v[124:125], v[124:125], v[184:185]
	v_pk_mul_f32 v[118:119], v[118:119], v[126:127]
	v_pk_mul_f32 v[120:121], v[120:121], v[128:129]
	v_pk_mul_f32 v[122:123], v[114:115], v[122:123]
	v_pk_mul_f32 v[124:125], v[116:117], v[124:125]
	v_cvt_pk_bf16_f32 v114, v118, v119
	v_cvt_pk_bf16_f32 v115, v120, v121
	v_cvt_pk_bf16_f32 v116, v122, v123
	v_cvt_pk_bf16_f32 v117, v124, v125
	global_store_dwordx4 v[174:175], v[114:117], off
	s_nop 0
	s_nop 0
	v_or_b32_e32 v115, 16, v166
	s_waitcnt vmcnt(7)
	v_mov_b32_e32 v114, v212
	v_fmamk_f32 v114, v114, 0x3a800000, v165
	v_mul_f32_e32 v116, 0x4b800000, v114
	v_cmp_gt_f32_e32 vcc, s74, v114
	s_nop 1
	v_cndmask_b32_e32 v114, v114, v116, vcc
	v_rsq_f32_e32 v116, v114
	v_mad_i64_i32 v[114:115], s[4:5], v115, s75, v[138:139]
	v_lshl_add_u64 v[114:115], v[114:115], 0, v[140:141]
	v_mul_f32_e32 v117, 0x45800000, v116
	v_cndmask_b32_e32 v116, v116, v117, vcc
	v_pk_mul_f32 v[110:111], v[110:111], v[116:117] op_sel_hi:[1,0]
	v_pk_mul_f32 v[112:113], v[112:113], v[116:117] op_sel_hi:[1,0]
	v_pk_mul_f32 v[106:107], v[106:107], v[116:117] op_sel_hi:[1,0]
	v_pk_mul_f32 v[108:109], v[108:109], v[116:117] op_sel_hi:[1,0]
	v_pk_mul_f32 v[102:103], v[102:103], v[116:117] op_sel_hi:[1,0]
	v_pk_mul_f32 v[104:105], v[104:105], v[116:117] op_sel_hi:[1,0]
	v_pk_mul_f32 v[98:99], v[98:99], v[116:117] op_sel_hi:[1,0]
	v_pk_mul_f32 v[100:101], v[100:101], v[116:117] op_sel_hi:[1,0]
	v_mul_f32_e32 v116, 0xbfb8aa3b, v110
	v_mul_f32_e32 v117, 0xbfb8aa3b, v111
	v_mul_f32_e32 v118, 0xbfb8aa3b, v112
	v_mul_f32_e32 v119, 0xbfb8aa3b, v113
	v_mul_f32_e32 v120, 0xbfb8aa3b, v106
	v_mul_f32_e32 v121, 0xbfb8aa3b, v107
	v_mul_f32_e32 v122, 0xbfb8aa3b, v108
	v_mul_f32_e32 v123, 0xbfb8aa3b, v109
	v_exp_f32_e32 v116, v116
	v_exp_f32_e32 v117, v117
	v_exp_f32_e32 v118, v118
	v_exp_f32_e32 v119, v119
	v_exp_f32_e32 v120, v120
	v_exp_f32_e32 v121, v121
	v_exp_f32_e32 v122, v122
	v_exp_f32_e32 v123, v123
	v_add_f32_e32 v116, 1.0, v116
	v_add_f32_e32 v117, 1.0, v117
	v_add_f32_e32 v118, 1.0, v118
	v_add_f32_e32 v119, 1.0, v119
	v_add_f32_e32 v120, 1.0, v120
	v_add_f32_e32 v121, 1.0, v121
	v_add_f32_e32 v122, 1.0, v122
	v_add_f32_e32 v123, 1.0, v123
	v_rcp_f32_e32 v116, v116
	v_rcp_f32_e32 v117, v117
	v_rcp_f32_e32 v118, v118
	v_rcp_f32_e32 v119, v119
	v_rcp_f32_e32 v120, v120
	v_rcp_f32_e32 v121, v121
	v_rcp_f32_e32 v122, v122
	v_rcp_f32_e32 v123, v123
	v_pk_mul_f32 v[110:111], v[110:111], v[116:117]
	v_pk_mul_f32 v[112:113], v[112:113], v[118:119]
	v_pk_mul_f32 v[106:107], v[106:107], v[120:121]
	v_pk_mul_f32 v[108:109], v[108:109], v[122:123]
	v_pk_mul_f32 v[102:103], v[102:103], v[110:111]
	v_pk_mul_f32 v[104:105], v[104:105], v[112:113]
	v_pk_mul_f32 v[106:107], v[98:99], v[106:107]
	v_pk_mul_f32 v[108:109], v[100:101], v[108:109]
	v_cvt_pk_bf16_f32 v98, v102, v103
	v_cvt_pk_bf16_f32 v99, v104, v105
	v_cvt_pk_bf16_f32 v100, v106, v107
	v_cvt_pk_bf16_f32 v101, v108, v109
	global_store_dwordx4 v[114:115], v[98:101], off
	s_nop 0
	s_nop 0
	v_or_b32_e32 v99, 32, v166
	s_waitcnt vmcnt(7)
	v_mov_b32_e32 v98, v213
	v_fmamk_f32 v98, v98, 0x3a800000, v165
	v_mul_f32_e32 v100, 0x4b800000, v98
	v_cmp_gt_f32_e32 vcc, s74, v98
	s_nop 1
	v_cndmask_b32_e32 v98, v98, v100, vcc
	v_rsq_f32_e32 v100, v98
	v_mad_i64_i32 v[98:99], s[4:5], v99, s75, v[138:139]
	v_lshl_add_u64 v[98:99], v[98:99], 0, v[140:141]
	v_mul_f32_e32 v101, 0x45800000, v100
	v_cndmask_b32_e32 v100, v100, v101, vcc
	v_pk_mul_f32 v[94:95], v[94:95], v[100:101] op_sel_hi:[1,0]
	v_pk_mul_f32 v[96:97], v[96:97], v[100:101] op_sel_hi:[1,0]
	v_pk_mul_f32 v[90:91], v[90:91], v[100:101] op_sel_hi:[1,0]
	v_pk_mul_f32 v[92:93], v[92:93], v[100:101] op_sel_hi:[1,0]
	v_pk_mul_f32 v[86:87], v[86:87], v[100:101] op_sel_hi:[1,0]
	v_pk_mul_f32 v[88:89], v[88:89], v[100:101] op_sel_hi:[1,0]
	v_pk_mul_f32 v[82:83], v[82:83], v[100:101] op_sel_hi:[1,0]
	v_pk_mul_f32 v[84:85], v[84:85], v[100:101] op_sel_hi:[1,0]
	v_mul_f32_e32 v100, 0xbfb8aa3b, v94
	v_mul_f32_e32 v101, 0xbfb8aa3b, v95
	v_mul_f32_e32 v102, 0xbfb8aa3b, v96
	v_mul_f32_e32 v103, 0xbfb8aa3b, v97
	v_mul_f32_e32 v104, 0xbfb8aa3b, v90
	v_mul_f32_e32 v105, 0xbfb8aa3b, v91
	v_mul_f32_e32 v106, 0xbfb8aa3b, v92
	v_mul_f32_e32 v107, 0xbfb8aa3b, v93
	v_exp_f32_e32 v100, v100
	v_exp_f32_e32 v101, v101
	v_exp_f32_e32 v102, v102
	v_exp_f32_e32 v103, v103
	v_exp_f32_e32 v104, v104
	v_exp_f32_e32 v105, v105
	v_exp_f32_e32 v106, v106
	v_exp_f32_e32 v107, v107
	v_add_f32_e32 v100, 1.0, v100
	v_add_f32_e32 v101, 1.0, v101
	v_add_f32_e32 v102, 1.0, v102
	v_add_f32_e32 v103, 1.0, v103
	v_add_f32_e32 v104, 1.0, v104
	v_add_f32_e32 v105, 1.0, v105
	v_add_f32_e32 v106, 1.0, v106
	v_add_f32_e32 v107, 1.0, v107
	v_rcp_f32_e32 v100, v100
	v_rcp_f32_e32 v101, v101
	v_rcp_f32_e32 v102, v102
	v_rcp_f32_e32 v103, v103
	v_rcp_f32_e32 v104, v104
	v_rcp_f32_e32 v105, v105
	v_rcp_f32_e32 v106, v106
	v_rcp_f32_e32 v107, v107
	v_pk_mul_f32 v[94:95], v[94:95], v[100:101]
	v_pk_mul_f32 v[96:97], v[96:97], v[102:103]
	v_pk_mul_f32 v[90:91], v[90:91], v[104:105]
	v_pk_mul_f32 v[92:93], v[92:93], v[106:107]
	v_pk_mul_f32 v[86:87], v[86:87], v[94:95]
	v_pk_mul_f32 v[88:89], v[88:89], v[96:97]
	v_pk_mul_f32 v[90:91], v[82:83], v[90:91]
	v_pk_mul_f32 v[92:93], v[84:85], v[92:93]
	v_cvt_pk_bf16_f32 v82, v86, v87
	v_cvt_pk_bf16_f32 v83, v88, v89
	v_cvt_pk_bf16_f32 v84, v90, v91
	v_cvt_pk_bf16_f32 v85, v92, v93
	global_store_dwordx4 v[98:99], v[82:85], off
	s_nop 0
	s_nop 0
	v_or_b32_e32 v83, 48, v166
	s_waitcnt vmcnt(7)
	v_mov_b32_e32 v82, v214
	v_fmamk_f32 v82, v82, 0x3a800000, v165
	v_mul_f32_e32 v84, 0x4b800000, v82
	v_cmp_gt_f32_e32 vcc, s74, v82
	s_nop 1
	v_cndmask_b32_e32 v82, v82, v84, vcc
	v_rsq_f32_e32 v84, v82
	v_mad_i64_i32 v[82:83], s[4:5], v83, s75, v[138:139]
	v_lshl_add_u64 v[82:83], v[82:83], 0, v[140:141]
	v_mul_f32_e32 v85, 0x45800000, v84
	v_cndmask_b32_e32 v84, v84, v85, vcc
	v_pk_mul_f32 v[78:79], v[78:79], v[84:85] op_sel_hi:[1,0]
	v_pk_mul_f32 v[80:81], v[80:81], v[84:85] op_sel_hi:[1,0]
	v_pk_mul_f32 v[74:75], v[74:75], v[84:85] op_sel_hi:[1,0]
	v_pk_mul_f32 v[76:77], v[76:77], v[84:85] op_sel_hi:[1,0]
	v_pk_mul_f32 v[70:71], v[70:71], v[84:85] op_sel_hi:[1,0]
	v_pk_mul_f32 v[72:73], v[72:73], v[84:85] op_sel_hi:[1,0]
	v_pk_mul_f32 v[66:67], v[66:67], v[84:85] op_sel_hi:[1,0]
	v_pk_mul_f32 v[68:69], v[68:69], v[84:85] op_sel_hi:[1,0]
	v_mul_f32_e32 v84, 0xbfb8aa3b, v78
	v_mul_f32_e32 v85, 0xbfb8aa3b, v79
	v_mul_f32_e32 v86, 0xbfb8aa3b, v80
	v_mul_f32_e32 v87, 0xbfb8aa3b, v81
	v_mul_f32_e32 v88, 0xbfb8aa3b, v74
	v_mul_f32_e32 v89, 0xbfb8aa3b, v75
	v_mul_f32_e32 v90, 0xbfb8aa3b, v76
	v_mul_f32_e32 v91, 0xbfb8aa3b, v77
	v_exp_f32_e32 v84, v84
	v_exp_f32_e32 v85, v85
	v_exp_f32_e32 v86, v86
	v_exp_f32_e32 v87, v87
	v_exp_f32_e32 v88, v88
	v_exp_f32_e32 v89, v89
	v_exp_f32_e32 v90, v90
	v_exp_f32_e32 v91, v91
	v_add_f32_e32 v84, 1.0, v84
	v_add_f32_e32 v85, 1.0, v85
	v_add_f32_e32 v86, 1.0, v86
	v_add_f32_e32 v87, 1.0, v87
	v_add_f32_e32 v88, 1.0, v88
	v_add_f32_e32 v89, 1.0, v89
	v_add_f32_e32 v90, 1.0, v90
	v_add_f32_e32 v91, 1.0, v91
	v_rcp_f32_e32 v84, v84
	v_rcp_f32_e32 v85, v85
	v_rcp_f32_e32 v86, v86
	v_rcp_f32_e32 v87, v87
	v_rcp_f32_e32 v88, v88
	v_rcp_f32_e32 v89, v89
	v_rcp_f32_e32 v90, v90
	v_rcp_f32_e32 v91, v91
	v_pk_mul_f32 v[78:79], v[78:79], v[84:85]
	v_pk_mul_f32 v[80:81], v[80:81], v[86:87]
	v_pk_mul_f32 v[74:75], v[74:75], v[88:89]
	v_pk_mul_f32 v[76:77], v[76:77], v[90:91]
	v_pk_mul_f32 v[70:71], v[70:71], v[78:79]
	v_pk_mul_f32 v[72:73], v[72:73], v[80:81]
	v_pk_mul_f32 v[74:75], v[66:67], v[74:75]
	v_pk_mul_f32 v[76:77], v[68:69], v[76:77]
	v_cvt_pk_bf16_f32 v66, v70, v71
	v_cvt_pk_bf16_f32 v67, v72, v73
	v_cvt_pk_bf16_f32 v68, v74, v75
	v_cvt_pk_bf16_f32 v69, v76, v77
	global_store_dwordx4 v[82:83], v[66:69], off
	s_nop 0
	s_nop 0
	v_add_u32_e32 v67, 0x80, v166
	s_waitcnt vmcnt(7)
	v_mov_b32_e32 v66, v215
	v_fmamk_f32 v66, v66, 0x3a800000, v165
	v_mul_f32_e32 v68, 0x4b800000, v66
	v_cmp_gt_f32_e32 vcc, s74, v66
	s_nop 1
	v_cndmask_b32_e32 v66, v66, v68, vcc
	v_rsq_f32_e32 v68, v66
	v_mad_i64_i32 v[66:67], s[4:5], v67, s75, v[138:139]
	v_lshl_add_u64 v[66:67], v[66:67], 0, v[140:141]
	v_mul_f32_e32 v69, 0x45800000, v68
	v_cndmask_b32_e32 v68, v68, v69, vcc
	v_pk_mul_f32 v[62:63], v[62:63], v[68:69] op_sel_hi:[1,0]
	v_pk_mul_f32 v[64:65], v[64:65], v[68:69] op_sel_hi:[1,0]
	v_pk_mul_f32 v[58:59], v[58:59], v[68:69] op_sel_hi:[1,0]
	v_pk_mul_f32 v[60:61], v[60:61], v[68:69] op_sel_hi:[1,0]
	v_pk_mul_f32 v[54:55], v[54:55], v[68:69] op_sel_hi:[1,0]
	v_pk_mul_f32 v[56:57], v[56:57], v[68:69] op_sel_hi:[1,0]
	v_pk_mul_f32 v[50:51], v[50:51], v[68:69] op_sel_hi:[1,0]
	v_pk_mul_f32 v[52:53], v[52:53], v[68:69] op_sel_hi:[1,0]
	v_mul_f32_e32 v68, 0xbfb8aa3b, v62
	v_mul_f32_e32 v69, 0xbfb8aa3b, v63
	v_mul_f32_e32 v70, 0xbfb8aa3b, v64
	v_mul_f32_e32 v71, 0xbfb8aa3b, v65
	v_mul_f32_e32 v72, 0xbfb8aa3b, v58
	v_mul_f32_e32 v73, 0xbfb8aa3b, v59
	v_mul_f32_e32 v74, 0xbfb8aa3b, v60
	v_mul_f32_e32 v75, 0xbfb8aa3b, v61
	v_exp_f32_e32 v68, v68
	v_exp_f32_e32 v69, v69
	v_exp_f32_e32 v70, v70
	v_exp_f32_e32 v71, v71
	v_exp_f32_e32 v72, v72
	v_exp_f32_e32 v73, v73
	v_exp_f32_e32 v74, v74
	v_exp_f32_e32 v75, v75
	v_add_f32_e32 v68, 1.0, v68
	v_add_f32_e32 v69, 1.0, v69
	v_add_f32_e32 v70, 1.0, v70
	v_add_f32_e32 v71, 1.0, v71
	v_add_f32_e32 v72, 1.0, v72
	v_add_f32_e32 v73, 1.0, v73
	v_add_f32_e32 v74, 1.0, v74
	v_add_f32_e32 v75, 1.0, v75
	v_rcp_f32_e32 v68, v68
	v_rcp_f32_e32 v69, v69
	v_rcp_f32_e32 v70, v70
	v_rcp_f32_e32 v71, v71
	v_rcp_f32_e32 v72, v72
	v_rcp_f32_e32 v73, v73
	v_rcp_f32_e32 v74, v74
	v_rcp_f32_e32 v75, v75
	v_pk_mul_f32 v[62:63], v[62:63], v[68:69]
	v_pk_mul_f32 v[64:65], v[64:65], v[70:71]
	v_pk_mul_f32 v[58:59], v[58:59], v[72:73]
	v_pk_mul_f32 v[60:61], v[60:61], v[74:75]
	v_pk_mul_f32 v[54:55], v[54:55], v[62:63]
	v_pk_mul_f32 v[56:57], v[56:57], v[64:65]
	v_pk_mul_f32 v[58:59], v[50:51], v[58:59]
	v_pk_mul_f32 v[60:61], v[52:53], v[60:61]
	v_cvt_pk_bf16_f32 v50, v54, v55
	v_cvt_pk_bf16_f32 v51, v56, v57
	v_cvt_pk_bf16_f32 v52, v58, v59
	v_cvt_pk_bf16_f32 v53, v60, v61
	global_store_dwordx4 v[66:67], v[50:53], off
	s_nop 0
	s_nop 0
	v_add_u32_e32 v51, 0x90, v166
	s_waitcnt vmcnt(7)
	v_mov_b32_e32 v50, v216
	v_fmamk_f32 v50, v50, 0x3a800000, v165
	v_mul_f32_e32 v52, 0x4b800000, v50
	v_cmp_gt_f32_e32 vcc, s74, v50
	s_nop 1
	v_cndmask_b32_e32 v50, v50, v52, vcc
	v_rsq_f32_e32 v52, v50
	v_mad_i64_i32 v[50:51], s[4:5], v51, s75, v[138:139]
	v_lshl_add_u64 v[50:51], v[50:51], 0, v[140:141]
	v_mul_f32_e32 v53, 0x45800000, v52
	v_cndmask_b32_e32 v52, v52, v53, vcc
	v_pk_mul_f32 v[46:47], v[46:47], v[52:53] op_sel_hi:[1,0]
	v_pk_mul_f32 v[48:49], v[48:49], v[52:53] op_sel_hi:[1,0]
	v_pk_mul_f32 v[42:43], v[42:43], v[52:53] op_sel_hi:[1,0]
	v_pk_mul_f32 v[44:45], v[44:45], v[52:53] op_sel_hi:[1,0]
	v_pk_mul_f32 v[38:39], v[38:39], v[52:53] op_sel_hi:[1,0]
	v_pk_mul_f32 v[40:41], v[40:41], v[52:53] op_sel_hi:[1,0]
	v_pk_mul_f32 v[34:35], v[34:35], v[52:53] op_sel_hi:[1,0]
	v_pk_mul_f32 v[36:37], v[36:37], v[52:53] op_sel_hi:[1,0]
	v_mul_f32_e32 v52, 0xbfb8aa3b, v46
	v_mul_f32_e32 v53, 0xbfb8aa3b, v47
	v_mul_f32_e32 v54, 0xbfb8aa3b, v48
	v_mul_f32_e32 v55, 0xbfb8aa3b, v49
	v_mul_f32_e32 v56, 0xbfb8aa3b, v42
	v_mul_f32_e32 v57, 0xbfb8aa3b, v43
	v_mul_f32_e32 v58, 0xbfb8aa3b, v44
	v_mul_f32_e32 v59, 0xbfb8aa3b, v45
	v_exp_f32_e32 v52, v52
	v_exp_f32_e32 v53, v53
	v_exp_f32_e32 v54, v54
	v_exp_f32_e32 v55, v55
	v_exp_f32_e32 v56, v56
	v_exp_f32_e32 v57, v57
	v_exp_f32_e32 v58, v58
	v_exp_f32_e32 v59, v59
	v_add_f32_e32 v52, 1.0, v52
	v_add_f32_e32 v53, 1.0, v53
	v_add_f32_e32 v54, 1.0, v54
	v_add_f32_e32 v55, 1.0, v55
	v_add_f32_e32 v56, 1.0, v56
	v_add_f32_e32 v57, 1.0, v57
	v_add_f32_e32 v58, 1.0, v58
	v_add_f32_e32 v59, 1.0, v59
	v_rcp_f32_e32 v52, v52
	v_rcp_f32_e32 v53, v53
	v_rcp_f32_e32 v54, v54
	v_rcp_f32_e32 v55, v55
	v_rcp_f32_e32 v56, v56
	v_rcp_f32_e32 v57, v57
	v_rcp_f32_e32 v58, v58
	v_rcp_f32_e32 v59, v59
	v_pk_mul_f32 v[46:47], v[46:47], v[52:53]
	v_pk_mul_f32 v[48:49], v[48:49], v[54:55]
	v_pk_mul_f32 v[42:43], v[42:43], v[56:57]
	v_pk_mul_f32 v[44:45], v[44:45], v[58:59]
	v_pk_mul_f32 v[38:39], v[38:39], v[46:47]
	v_pk_mul_f32 v[40:41], v[40:41], v[48:49]
	v_pk_mul_f32 v[42:43], v[34:35], v[42:43]
	v_pk_mul_f32 v[44:45], v[36:37], v[44:45]
	v_cvt_pk_bf16_f32 v34, v38, v39
	v_cvt_pk_bf16_f32 v35, v40, v41
	v_cvt_pk_bf16_f32 v36, v42, v43
	v_cvt_pk_bf16_f32 v37, v44, v45
	global_store_dwordx4 v[50:51], v[34:37], off
	s_nop 0
	s_nop 0
	v_add_u32_e32 v35, 0xa0, v166
	s_waitcnt vmcnt(7)
	v_mov_b32_e32 v34, v217
	v_fmamk_f32 v34, v34, 0x3a800000, v165
	v_mul_f32_e32 v36, 0x4b800000, v34
	v_cmp_gt_f32_e32 vcc, s74, v34
	s_nop 1
	v_cndmask_b32_e32 v34, v34, v36, vcc
	v_rsq_f32_e32 v36, v34
	v_mad_i64_i32 v[34:35], s[4:5], v35, s75, v[138:139]
	v_lshl_add_u64 v[34:35], v[34:35], 0, v[140:141]
	v_mul_f32_e32 v37, 0x45800000, v36
	v_cndmask_b32_e32 v36, v36, v37, vcc
	v_pk_mul_f32 v[30:31], v[30:31], v[36:37] op_sel_hi:[1,0]
	v_pk_mul_f32 v[32:33], v[32:33], v[36:37] op_sel_hi:[1,0]
	v_pk_mul_f32 v[26:27], v[26:27], v[36:37] op_sel_hi:[1,0]
	v_pk_mul_f32 v[28:29], v[28:29], v[36:37] op_sel_hi:[1,0]
	v_pk_mul_f32 v[22:23], v[22:23], v[36:37] op_sel_hi:[1,0]
	v_pk_mul_f32 v[24:25], v[24:25], v[36:37] op_sel_hi:[1,0]
	v_pk_mul_f32 v[18:19], v[18:19], v[36:37] op_sel_hi:[1,0]
	v_pk_mul_f32 v[20:21], v[20:21], v[36:37] op_sel_hi:[1,0]
	v_mul_f32_e32 v36, 0xbfb8aa3b, v30
	v_mul_f32_e32 v37, 0xbfb8aa3b, v31
	v_mul_f32_e32 v38, 0xbfb8aa3b, v32
	v_mul_f32_e32 v39, 0xbfb8aa3b, v33
	v_mul_f32_e32 v40, 0xbfb8aa3b, v26
	v_mul_f32_e32 v41, 0xbfb8aa3b, v27
	v_mul_f32_e32 v42, 0xbfb8aa3b, v28
	v_mul_f32_e32 v43, 0xbfb8aa3b, v29
	v_exp_f32_e32 v36, v36
	v_exp_f32_e32 v37, v37
	v_exp_f32_e32 v38, v38
	v_exp_f32_e32 v39, v39
	v_exp_f32_e32 v40, v40
	v_exp_f32_e32 v41, v41
	v_exp_f32_e32 v42, v42
	v_exp_f32_e32 v43, v43
	v_add_f32_e32 v36, 1.0, v36
	v_add_f32_e32 v37, 1.0, v37
	v_add_f32_e32 v38, 1.0, v38
	v_add_f32_e32 v39, 1.0, v39
	v_add_f32_e32 v40, 1.0, v40
	v_add_f32_e32 v41, 1.0, v41
	v_add_f32_e32 v42, 1.0, v42
	v_add_f32_e32 v43, 1.0, v43
	v_rcp_f32_e32 v36, v36
	v_rcp_f32_e32 v37, v37
	v_rcp_f32_e32 v38, v38
	v_rcp_f32_e32 v39, v39
	v_rcp_f32_e32 v40, v40
	v_rcp_f32_e32 v41, v41
	v_rcp_f32_e32 v42, v42
	v_rcp_f32_e32 v43, v43
	v_pk_mul_f32 v[30:31], v[30:31], v[36:37]
	v_pk_mul_f32 v[32:33], v[32:33], v[38:39]
	v_pk_mul_f32 v[26:27], v[26:27], v[40:41]
	v_pk_mul_f32 v[28:29], v[28:29], v[42:43]
	v_pk_mul_f32 v[22:23], v[22:23], v[30:31]
	v_pk_mul_f32 v[24:25], v[24:25], v[32:33]
	v_pk_mul_f32 v[26:27], v[18:19], v[26:27]
	v_pk_mul_f32 v[28:29], v[20:21], v[28:29]
	v_cvt_pk_bf16_f32 v18, v22, v23
	v_cvt_pk_bf16_f32 v19, v24, v25
	v_cvt_pk_bf16_f32 v20, v26, v27
	v_cvt_pk_bf16_f32 v21, v28, v29
	global_store_dwordx4 v[34:35], v[18:21], off
	s_nop 0
	s_andn2_b64 vcc, exec, s[0:1]
	v_add_u32_e32 v19, 0xb0, v166
	s_mov_b64 s[0:1], -1
	s_waitcnt vmcnt(7)
	v_mov_b32_e32 v18, v218
	v_fmamk_f32 v18, v18, 0x3a800000, v165
	v_mul_f32_e32 v20, 0x4b800000, v18
	v_cmp_gt_f32_e64 s[4:5], s74, v18
	s_nop 1
	v_cndmask_b32_e64 v18, v18, v20, s[4:5]
	v_rsq_f32_e32 v20, v18
	v_mad_i64_i32 v[18:19], s[6:7], v19, s75, v[138:139]
	v_lshl_add_u64 v[18:19], v[18:19], 0, v[140:141]
	v_mul_f32_e32 v21, 0x45800000, v20
	v_cndmask_b32_e64 v20, v20, v21, s[4:5]
	v_pk_mul_f32 v[14:15], v[14:15], v[20:21] op_sel_hi:[1,0]
	v_pk_mul_f32 v[16:17], v[16:17], v[20:21] op_sel_hi:[1,0]
	v_pk_mul_f32 v[10:11], v[10:11], v[20:21] op_sel_hi:[1,0]
	v_pk_mul_f32 v[12:13], v[12:13], v[20:21] op_sel_hi:[1,0]
	v_pk_mul_f32 v[6:7], v[6:7], v[20:21] op_sel_hi:[1,0]
	v_pk_mul_f32 v[8:9], v[8:9], v[20:21] op_sel_hi:[1,0]
	v_pk_mul_f32 v[2:3], v[2:3], v[20:21] op_sel_hi:[1,0]
	v_pk_mul_f32 v[4:5], v[4:5], v[20:21] op_sel_hi:[1,0]
	v_mul_f32_e32 v20, 0xbfb8aa3b, v14
	v_mul_f32_e32 v21, 0xbfb8aa3b, v15
	v_mul_f32_e32 v22, 0xbfb8aa3b, v16
	v_mul_f32_e32 v23, 0xbfb8aa3b, v17
	v_mul_f32_e32 v24, 0xbfb8aa3b, v10
	v_mul_f32_e32 v25, 0xbfb8aa3b, v11
	v_mul_f32_e32 v26, 0xbfb8aa3b, v12
	v_mul_f32_e32 v27, 0xbfb8aa3b, v13
	v_exp_f32_e32 v20, v20
	v_exp_f32_e32 v21, v21
	v_exp_f32_e32 v22, v22
	v_exp_f32_e32 v23, v23
	v_exp_f32_e32 v24, v24
	v_exp_f32_e32 v25, v25
	v_exp_f32_e32 v26, v26
	v_exp_f32_e32 v27, v27
	v_add_f32_e32 v20, 1.0, v20
	v_add_f32_e32 v21, 1.0, v21
	v_add_f32_e32 v22, 1.0, v22
	v_add_f32_e32 v23, 1.0, v23
	v_add_f32_e32 v24, 1.0, v24
	v_add_f32_e32 v25, 1.0, v25
	v_add_f32_e32 v26, 1.0, v26
	v_add_f32_e32 v27, 1.0, v27
	v_rcp_f32_e32 v20, v20
	v_rcp_f32_e32 v21, v21
	v_rcp_f32_e32 v22, v22
	v_rcp_f32_e32 v23, v23
	v_rcp_f32_e32 v24, v24
	v_rcp_f32_e32 v25, v25
	v_rcp_f32_e32 v26, v26
	v_rcp_f32_e32 v27, v27
	v_pk_mul_f32 v[14:15], v[14:15], v[20:21]
	v_pk_mul_f32 v[16:17], v[16:17], v[22:23]
	v_pk_mul_f32 v[10:11], v[10:11], v[24:25]
	v_pk_mul_f32 v[12:13], v[12:13], v[26:27]
	v_pk_mul_f32 v[6:7], v[6:7], v[14:15]
	v_pk_mul_f32 v[8:9], v[8:9], v[16:17]
	v_pk_mul_f32 v[10:11], v[2:3], v[10:11]
	v_pk_mul_f32 v[12:13], v[4:5], v[12:13]
	v_cvt_pk_bf16_f32 v2, v6, v7
	v_cvt_pk_bf16_f32 v3, v8, v9
	v_cvt_pk_bf16_f32 v4, v10, v11
	v_cvt_pk_bf16_f32 v5, v12, v13
	global_store_dwordx4 v[18:19], v[2:5], off
	s_cbranch_vccnz .LBB0_1516
	s_andn2_b64 vcc, exec, s[18:19]
	s_cbranch_vccnz .LBB0_1515
	s_barrier
	s_branch .LBB0_1515

.LBB0_1792:
	s_cmp_lt_i32 s4, 11
	s_cselect_b32 s6, 21, 42
	s_add_i32 s6, s6, s4
	v_lshl_add_u32 v138, s6, 8, v144
	v_ashrrev_i32_e32 v139, 31, v138
	v_lshl_add_u64 v[142:143], v[138:139], 2, s[56:57]
	global_load_dword v164, v[142:143], off
	global_load_dword v212, v[142:143], off offset:64
	global_load_dword v213, v[142:143], off offset:128
	global_load_dword v214, v[142:143], off offset:192
	global_load_dword v215, v[142:143], off offset:512
	global_load_dword v216, v[142:143], off offset:576
	global_load_dword v217, v[142:143], off offset:640
	global_load_dword v218, v[142:143], off offset:704
	v_lshl_or_b32 v140, s5, 7, v154
	v_lshl_add_u32 v163, s4, 8, v144
	v_mov_b64_e32 v[138:139], s[12:13]
	v_ashrrev_i32_e32 v141, 31, v140
	v_lshlrev_b64 v[140:141], 1, v[140:141]
	s_waitcnt vmcnt(7)
	v_fmamk_f32 v164, v164, 0x3a800000, v161
	v_mul_f32_e32 v165, 0x4b800000, v164
	v_cmp_gt_f32_e32 vcc, s58, v164
	s_nop 1
	v_cndmask_b32_e32 v164, v164, v165, vcc
	v_rsq_f32_e32 v166, v164
	v_mad_i64_i32 v[164:165], s[4:5], v163, s59, v[138:139]
	v_lshl_add_u64 v[164:165], v[164:165], 0, v[140:141]
	v_mul_f32_e32 v167, 0x45800000, v166
	v_cndmask_b32_e32 v166, v166, v167, vcc
	v_pk_mul_f32 v[126:127], v[126:127], v[166:167] op_sel_hi:[1,0]
	v_pk_mul_f32 v[128:129], v[128:129], v[166:167] op_sel_hi:[1,0]
	v_pk_mul_f32 v[122:123], v[122:123], v[166:167] op_sel_hi:[1,0]
	v_pk_mul_f32 v[124:125], v[124:125], v[166:167] op_sel_hi:[1,0]
	v_pk_mul_f32 v[118:119], v[118:119], v[166:167] op_sel_hi:[1,0]
	v_pk_mul_f32 v[120:121], v[120:121], v[166:167] op_sel_hi:[1,0]
	v_pk_mul_f32 v[114:115], v[114:115], v[166:167] op_sel_hi:[1,0]
	v_pk_mul_f32 v[116:117], v[116:117], v[166:167] op_sel_hi:[1,0]
	v_mul_f32_e32 v166, 0xbfb8aa3b, v126
	v_mul_f32_e32 v167, 0xbfb8aa3b, v127
	v_mul_f32_e32 v168, 0xbfb8aa3b, v128
	v_mul_f32_e32 v170, 0xbfb8aa3b, v129
	v_mul_f32_e32 v171, 0xbfb8aa3b, v122
	v_mul_f32_e32 v172, 0xbfb8aa3b, v123
	v_mul_f32_e32 v174, 0xbfb8aa3b, v124
	v_mul_f32_e32 v175, 0xbfb8aa3b, v125
	v_exp_f32_e32 v166, v166
	v_exp_f32_e32 v167, v167
	v_exp_f32_e32 v168, v168
	v_exp_f32_e32 v170, v170
	v_exp_f32_e32 v171, v171
	v_exp_f32_e32 v172, v172
	v_exp_f32_e32 v174, v174
	v_exp_f32_e32 v175, v175
	v_add_f32_e32 v166, 1.0, v166
	v_add_f32_e32 v167, 1.0, v167
	v_add_f32_e32 v168, 1.0, v168
	v_add_f32_e32 v176, 1.0, v170
	v_add_f32_e32 v177, 1.0, v171
	v_add_f32_e32 v172, 1.0, v172
	v_add_f32_e32 v178, 1.0, v174
	v_add_f32_e32 v180, 1.0, v175
	v_rcp_f32_e32 v166, v166
	v_rcp_f32_e32 v167, v167
	v_rcp_f32_e32 v170, v168
	v_rcp_f32_e32 v171, v176
	v_rcp_f32_e32 v174, v177
	v_rcp_f32_e32 v175, v172
	v_rcp_f32_e32 v176, v178
	v_rcp_f32_e32 v177, v180
	v_pk_mul_f32 v[126:127], v[126:127], v[166:167]
	v_pk_mul_f32 v[128:129], v[128:129], v[170:171]
	v_pk_mul_f32 v[122:123], v[122:123], v[174:175]
	v_pk_mul_f32 v[124:125], v[124:125], v[176:177]
	v_pk_mul_f32 v[118:119], v[118:119], v[126:127]
	v_pk_mul_f32 v[120:121], v[120:121], v[128:129]
	v_pk_mul_f32 v[122:123], v[114:115], v[122:123]
	v_pk_mul_f32 v[124:125], v[116:117], v[124:125]
	v_cvt_pk_bf16_f32 v114, v118, v119
	v_cvt_pk_bf16_f32 v115, v120, v121
	v_cvt_pk_bf16_f32 v116, v122, v123
	v_cvt_pk_bf16_f32 v117, v124, v125
	global_store_dwordx4 v[164:165], v[114:117], off
	s_nop 0
	s_nop 0
	v_or_b32_e32 v115, 16, v163
	s_waitcnt vmcnt(7)
	v_mov_b32_e32 v114, v212
	v_fmamk_f32 v114, v114, 0x3a800000, v161
	v_mul_f32_e32 v116, 0x4b800000, v114
	v_cmp_gt_f32_e32 vcc, s58, v114
	s_nop 1
	v_cndmask_b32_e32 v114, v114, v116, vcc
	v_rsq_f32_e32 v116, v114
	v_mad_i64_i32 v[114:115], s[4:5], v115, s59, v[138:139]
	v_lshl_add_u64 v[114:115], v[114:115], 0, v[140:141]
	v_mul_f32_e32 v117, 0x45800000, v116
	v_cndmask_b32_e32 v116, v116, v117, vcc
	v_pk_mul_f32 v[110:111], v[110:111], v[116:117] op_sel_hi:[1,0]
	v_pk_mul_f32 v[112:113], v[112:113], v[116:117] op_sel_hi:[1,0]
	v_pk_mul_f32 v[106:107], v[106:107], v[116:117] op_sel_hi:[1,0]
	v_pk_mul_f32 v[108:109], v[108:109], v[116:117] op_sel_hi:[1,0]
	v_pk_mul_f32 v[102:103], v[102:103], v[116:117] op_sel_hi:[1,0]
	v_pk_mul_f32 v[104:105], v[104:105], v[116:117] op_sel_hi:[1,0]
	v_pk_mul_f32 v[98:99], v[98:99], v[116:117] op_sel_hi:[1,0]
	v_pk_mul_f32 v[100:101], v[100:101], v[116:117] op_sel_hi:[1,0]
	v_mul_f32_e32 v116, 0xbfb8aa3b, v110
	v_mul_f32_e32 v117, 0xbfb8aa3b, v111
	v_mul_f32_e32 v118, 0xbfb8aa3b, v112
	v_mul_f32_e32 v119, 0xbfb8aa3b, v113
	v_mul_f32_e32 v120, 0xbfb8aa3b, v106
	v_mul_f32_e32 v121, 0xbfb8aa3b, v107
	v_mul_f32_e32 v122, 0xbfb8aa3b, v108
	v_mul_f32_e32 v123, 0xbfb8aa3b, v109
	v_exp_f32_e32 v116, v116
	v_exp_f32_e32 v117, v117
	v_exp_f32_e32 v118, v118
	v_exp_f32_e32 v119, v119
	v_exp_f32_e32 v120, v120
	v_exp_f32_e32 v121, v121
	v_exp_f32_e32 v122, v122
	v_exp_f32_e32 v123, v123
	v_add_f32_e32 v116, 1.0, v116
	v_add_f32_e32 v117, 1.0, v117
	v_add_f32_e32 v118, 1.0, v118
	v_add_f32_e32 v119, 1.0, v119
	v_add_f32_e32 v120, 1.0, v120
	v_add_f32_e32 v121, 1.0, v121
	v_add_f32_e32 v122, 1.0, v122
	v_add_f32_e32 v123, 1.0, v123
	v_rcp_f32_e32 v116, v116
	v_rcp_f32_e32 v117, v117
	v_rcp_f32_e32 v118, v118
	v_rcp_f32_e32 v119, v119
	v_rcp_f32_e32 v120, v120
	v_rcp_f32_e32 v121, v121
	v_rcp_f32_e32 v122, v122
	v_rcp_f32_e32 v123, v123
	v_pk_mul_f32 v[110:111], v[110:111], v[116:117]
	v_pk_mul_f32 v[112:113], v[112:113], v[118:119]
	v_pk_mul_f32 v[106:107], v[106:107], v[120:121]
	v_pk_mul_f32 v[108:109], v[108:109], v[122:123]
	v_pk_mul_f32 v[102:103], v[102:103], v[110:111]
	v_pk_mul_f32 v[104:105], v[104:105], v[112:113]
	v_pk_mul_f32 v[106:107], v[98:99], v[106:107]
	v_pk_mul_f32 v[108:109], v[100:101], v[108:109]
	v_cvt_pk_bf16_f32 v98, v102, v103
	v_cvt_pk_bf16_f32 v99, v104, v105
	v_cvt_pk_bf16_f32 v100, v106, v107
	v_cvt_pk_bf16_f32 v101, v108, v109
	global_store_dwordx4 v[114:115], v[98:101], off
	s_nop 0
	s_nop 0
	v_or_b32_e32 v99, 32, v163
	s_waitcnt vmcnt(7)
	v_mov_b32_e32 v98, v213
	v_fmamk_f32 v98, v98, 0x3a800000, v161
	v_mul_f32_e32 v100, 0x4b800000, v98
	v_cmp_gt_f32_e32 vcc, s58, v98
	s_nop 1
	v_cndmask_b32_e32 v98, v98, v100, vcc
	v_rsq_f32_e32 v100, v98
	v_mad_i64_i32 v[98:99], s[4:5], v99, s59, v[138:139]
	v_lshl_add_u64 v[98:99], v[98:99], 0, v[140:141]
	v_mul_f32_e32 v101, 0x45800000, v100
	v_cndmask_b32_e32 v100, v100, v101, vcc
	v_pk_mul_f32 v[94:95], v[94:95], v[100:101] op_sel_hi:[1,0]
	v_pk_mul_f32 v[96:97], v[96:97], v[100:101] op_sel_hi:[1,0]
	v_pk_mul_f32 v[90:91], v[90:91], v[100:101] op_sel_hi:[1,0]
	v_pk_mul_f32 v[92:93], v[92:93], v[100:101] op_sel_hi:[1,0]
	v_pk_mul_f32 v[86:87], v[86:87], v[100:101] op_sel_hi:[1,0]
	v_pk_mul_f32 v[88:89], v[88:89], v[100:101] op_sel_hi:[1,0]
	v_pk_mul_f32 v[82:83], v[82:83], v[100:101] op_sel_hi:[1,0]
	v_pk_mul_f32 v[84:85], v[84:85], v[100:101] op_sel_hi:[1,0]
	v_mul_f32_e32 v100, 0xbfb8aa3b, v94
	v_mul_f32_e32 v101, 0xbfb8aa3b, v95
	v_mul_f32_e32 v102, 0xbfb8aa3b, v96
	v_mul_f32_e32 v103, 0xbfb8aa3b, v97
	v_mul_f32_e32 v104, 0xbfb8aa3b, v90
	v_mul_f32_e32 v105, 0xbfb8aa3b, v91
	v_mul_f32_e32 v106, 0xbfb8aa3b, v92
	v_mul_f32_e32 v107, 0xbfb8aa3b, v93
	v_exp_f32_e32 v100, v100
	v_exp_f32_e32 v101, v101
	v_exp_f32_e32 v102, v102
	v_exp_f32_e32 v103, v103
	v_exp_f32_e32 v104, v104
	v_exp_f32_e32 v105, v105
	v_exp_f32_e32 v106, v106
	v_exp_f32_e32 v107, v107
	v_add_f32_e32 v100, 1.0, v100
	v_add_f32_e32 v101, 1.0, v101
	v_add_f32_e32 v102, 1.0, v102
	v_add_f32_e32 v103, 1.0, v103
	v_add_f32_e32 v104, 1.0, v104
	v_add_f32_e32 v105, 1.0, v105
	v_add_f32_e32 v106, 1.0, v106
	v_add_f32_e32 v107, 1.0, v107
	v_rcp_f32_e32 v100, v100
	v_rcp_f32_e32 v101, v101
	v_rcp_f32_e32 v102, v102
	v_rcp_f32_e32 v103, v103
	v_rcp_f32_e32 v104, v104
	v_rcp_f32_e32 v105, v105
	v_rcp_f32_e32 v106, v106
	v_rcp_f32_e32 v107, v107
	v_pk_mul_f32 v[94:95], v[94:95], v[100:101]
	v_pk_mul_f32 v[96:97], v[96:97], v[102:103]
	v_pk_mul_f32 v[90:91], v[90:91], v[104:105]
	v_pk_mul_f32 v[92:93], v[92:93], v[106:107]
	v_pk_mul_f32 v[86:87], v[86:87], v[94:95]
	v_pk_mul_f32 v[88:89], v[88:89], v[96:97]
	v_pk_mul_f32 v[90:91], v[82:83], v[90:91]
	v_pk_mul_f32 v[92:93], v[84:85], v[92:93]
	v_cvt_pk_bf16_f32 v82, v86, v87
	v_cvt_pk_bf16_f32 v83, v88, v89
	v_cvt_pk_bf16_f32 v84, v90, v91
	v_cvt_pk_bf16_f32 v85, v92, v93
	global_store_dwordx4 v[98:99], v[82:85], off
	s_nop 0
	s_nop 0
	v_or_b32_e32 v83, 48, v163
	s_waitcnt vmcnt(7)
	v_mov_b32_e32 v82, v214
	v_fmamk_f32 v82, v82, 0x3a800000, v161
	v_mul_f32_e32 v84, 0x4b800000, v82
	v_cmp_gt_f32_e32 vcc, s58, v82
	s_nop 1
	v_cndmask_b32_e32 v82, v82, v84, vcc
	v_rsq_f32_e32 v84, v82
	v_mad_i64_i32 v[82:83], s[4:5], v83, s59, v[138:139]
	v_lshl_add_u64 v[82:83], v[82:83], 0, v[140:141]
	v_mul_f32_e32 v85, 0x45800000, v84
	v_cndmask_b32_e32 v84, v84, v85, vcc
	v_pk_mul_f32 v[78:79], v[78:79], v[84:85] op_sel_hi:[1,0]
	v_pk_mul_f32 v[80:81], v[80:81], v[84:85] op_sel_hi:[1,0]
	v_pk_mul_f32 v[74:75], v[74:75], v[84:85] op_sel_hi:[1,0]
	v_pk_mul_f32 v[76:77], v[76:77], v[84:85] op_sel_hi:[1,0]
	v_pk_mul_f32 v[70:71], v[70:71], v[84:85] op_sel_hi:[1,0]
	v_pk_mul_f32 v[72:73], v[72:73], v[84:85] op_sel_hi:[1,0]
	v_pk_mul_f32 v[66:67], v[66:67], v[84:85] op_sel_hi:[1,0]
	v_pk_mul_f32 v[68:69], v[68:69], v[84:85] op_sel_hi:[1,0]
	v_mul_f32_e32 v84, 0xbfb8aa3b, v78
	v_mul_f32_e32 v85, 0xbfb8aa3b, v79
	v_mul_f32_e32 v86, 0xbfb8aa3b, v80
	v_mul_f32_e32 v87, 0xbfb8aa3b, v81
	v_mul_f32_e32 v88, 0xbfb8aa3b, v74
	v_mul_f32_e32 v89, 0xbfb8aa3b, v75
	v_mul_f32_e32 v90, 0xbfb8aa3b, v76
	v_mul_f32_e32 v91, 0xbfb8aa3b, v77
	v_exp_f32_e32 v84, v84
	v_exp_f32_e32 v85, v85
	v_exp_f32_e32 v86, v86
	v_exp_f32_e32 v87, v87
	v_exp_f32_e32 v88, v88
	v_exp_f32_e32 v89, v89
	v_exp_f32_e32 v90, v90
	v_exp_f32_e32 v91, v91
	v_add_f32_e32 v84, 1.0, v84
	v_add_f32_e32 v85, 1.0, v85
	v_add_f32_e32 v86, 1.0, v86
	v_add_f32_e32 v87, 1.0, v87
	v_add_f32_e32 v88, 1.0, v88
	v_add_f32_e32 v89, 1.0, v89
	v_add_f32_e32 v90, 1.0, v90
	v_add_f32_e32 v91, 1.0, v91
	v_rcp_f32_e32 v84, v84
	v_rcp_f32_e32 v85, v85
	v_rcp_f32_e32 v86, v86
	v_rcp_f32_e32 v87, v87
	v_rcp_f32_e32 v88, v88
	v_rcp_f32_e32 v89, v89
	v_rcp_f32_e32 v90, v90
	v_rcp_f32_e32 v91, v91
	v_pk_mul_f32 v[78:79], v[78:79], v[84:85]
	v_pk_mul_f32 v[80:81], v[80:81], v[86:87]
	v_pk_mul_f32 v[74:75], v[74:75], v[88:89]
	v_pk_mul_f32 v[76:77], v[76:77], v[90:91]
	v_pk_mul_f32 v[70:71], v[70:71], v[78:79]
	v_pk_mul_f32 v[72:73], v[72:73], v[80:81]
	v_pk_mul_f32 v[74:75], v[66:67], v[74:75]
	v_pk_mul_f32 v[76:77], v[68:69], v[76:77]
	v_cvt_pk_bf16_f32 v66, v70, v71
	v_cvt_pk_bf16_f32 v67, v72, v73
	v_cvt_pk_bf16_f32 v68, v74, v75
	v_cvt_pk_bf16_f32 v69, v76, v77
	global_store_dwordx4 v[82:83], v[66:69], off
	s_nop 0
	s_nop 0
	v_add_u32_e32 v67, 0x80, v163
	s_waitcnt vmcnt(7)
	v_mov_b32_e32 v66, v215
	v_fmamk_f32 v66, v66, 0x3a800000, v161
	v_mul_f32_e32 v68, 0x4b800000, v66
	v_cmp_gt_f32_e32 vcc, s58, v66
	s_nop 1
	v_cndmask_b32_e32 v66, v66, v68, vcc
	v_rsq_f32_e32 v68, v66
	v_mad_i64_i32 v[66:67], s[4:5], v67, s59, v[138:139]
	v_lshl_add_u64 v[66:67], v[66:67], 0, v[140:141]
	v_mul_f32_e32 v69, 0x45800000, v68
	v_cndmask_b32_e32 v68, v68, v69, vcc
	v_pk_mul_f32 v[62:63], v[62:63], v[68:69] op_sel_hi:[1,0]
	v_pk_mul_f32 v[64:65], v[64:65], v[68:69] op_sel_hi:[1,0]
	v_pk_mul_f32 v[58:59], v[58:59], v[68:69] op_sel_hi:[1,0]
	v_pk_mul_f32 v[60:61], v[60:61], v[68:69] op_sel_hi:[1,0]
	v_pk_mul_f32 v[54:55], v[54:55], v[68:69] op_sel_hi:[1,0]
	v_pk_mul_f32 v[56:57], v[56:57], v[68:69] op_sel_hi:[1,0]
	v_pk_mul_f32 v[50:51], v[50:51], v[68:69] op_sel_hi:[1,0]
	v_pk_mul_f32 v[52:53], v[52:53], v[68:69] op_sel_hi:[1,0]
	v_mul_f32_e32 v68, 0xbfb8aa3b, v62
	v_mul_f32_e32 v69, 0xbfb8aa3b, v63
	v_mul_f32_e32 v70, 0xbfb8aa3b, v64
	v_mul_f32_e32 v71, 0xbfb8aa3b, v65
	v_mul_f32_e32 v72, 0xbfb8aa3b, v58
	v_mul_f32_e32 v73, 0xbfb8aa3b, v59
	v_mul_f32_e32 v74, 0xbfb8aa3b, v60
	v_mul_f32_e32 v75, 0xbfb8aa3b, v61
	v_exp_f32_e32 v68, v68
	v_exp_f32_e32 v69, v69
	v_exp_f32_e32 v70, v70
	v_exp_f32_e32 v71, v71
	v_exp_f32_e32 v72, v72
	v_exp_f32_e32 v73, v73
	v_exp_f32_e32 v74, v74
	v_exp_f32_e32 v75, v75
	v_add_f32_e32 v68, 1.0, v68
	v_add_f32_e32 v69, 1.0, v69
	v_add_f32_e32 v70, 1.0, v70
	v_add_f32_e32 v71, 1.0, v71
	v_add_f32_e32 v72, 1.0, v72
	v_add_f32_e32 v73, 1.0, v73
	v_add_f32_e32 v74, 1.0, v74
	v_add_f32_e32 v75, 1.0, v75
	v_rcp_f32_e32 v68, v68
	v_rcp_f32_e32 v69, v69
	v_rcp_f32_e32 v70, v70
	v_rcp_f32_e32 v71, v71
	v_rcp_f32_e32 v72, v72
	v_rcp_f32_e32 v73, v73
	v_rcp_f32_e32 v74, v74
	v_rcp_f32_e32 v75, v75
	v_pk_mul_f32 v[62:63], v[62:63], v[68:69]
	v_pk_mul_f32 v[64:65], v[64:65], v[70:71]
	v_pk_mul_f32 v[58:59], v[58:59], v[72:73]
	v_pk_mul_f32 v[60:61], v[60:61], v[74:75]
	v_pk_mul_f32 v[54:55], v[54:55], v[62:63]
	v_pk_mul_f32 v[56:57], v[56:57], v[64:65]
	v_pk_mul_f32 v[58:59], v[50:51], v[58:59]
	v_pk_mul_f32 v[60:61], v[52:53], v[60:61]
	v_cvt_pk_bf16_f32 v50, v54, v55
	v_cvt_pk_bf16_f32 v51, v56, v57
	v_cvt_pk_bf16_f32 v52, v58, v59
	v_cvt_pk_bf16_f32 v53, v60, v61
	global_store_dwordx4 v[66:67], v[50:53], off
	s_nop 0
	s_nop 0
	v_add_u32_e32 v51, 0x90, v163
	s_waitcnt vmcnt(7)
	v_mov_b32_e32 v50, v216
	v_fmamk_f32 v50, v50, 0x3a800000, v161
	v_mul_f32_e32 v52, 0x4b800000, v50
	v_cmp_gt_f32_e32 vcc, s58, v50
	s_nop 1
	v_cndmask_b32_e32 v50, v50, v52, vcc
	v_rsq_f32_e32 v52, v50
	v_mad_i64_i32 v[50:51], s[4:5], v51, s59, v[138:139]
	v_lshl_add_u64 v[50:51], v[50:51], 0, v[140:141]
	v_mul_f32_e32 v53, 0x45800000, v52
	v_cndmask_b32_e32 v52, v52, v53, vcc
	v_pk_mul_f32 v[46:47], v[46:47], v[52:53] op_sel_hi:[1,0]
	v_pk_mul_f32 v[48:49], v[48:49], v[52:53] op_sel_hi:[1,0]
	v_pk_mul_f32 v[42:43], v[42:43], v[52:53] op_sel_hi:[1,0]
	v_pk_mul_f32 v[44:45], v[44:45], v[52:53] op_sel_hi:[1,0]
	v_pk_mul_f32 v[38:39], v[38:39], v[52:53] op_sel_hi:[1,0]
	v_pk_mul_f32 v[40:41], v[40:41], v[52:53] op_sel_hi:[1,0]
	v_pk_mul_f32 v[34:35], v[34:35], v[52:53] op_sel_hi:[1,0]
	v_pk_mul_f32 v[36:37], v[36:37], v[52:53] op_sel_hi:[1,0]
	v_mul_f32_e32 v52, 0xbfb8aa3b, v46
	v_mul_f32_e32 v53, 0xbfb8aa3b, v47
	v_mul_f32_e32 v54, 0xbfb8aa3b, v48
	v_mul_f32_e32 v55, 0xbfb8aa3b, v49
	v_mul_f32_e32 v56, 0xbfb8aa3b, v42
	v_mul_f32_e32 v57, 0xbfb8aa3b, v43
	v_mul_f32_e32 v58, 0xbfb8aa3b, v44
	v_mul_f32_e32 v59, 0xbfb8aa3b, v45
	v_exp_f32_e32 v52, v52
	v_exp_f32_e32 v53, v53
	v_exp_f32_e32 v54, v54
	v_exp_f32_e32 v55, v55
	v_exp_f32_e32 v56, v56
	v_exp_f32_e32 v57, v57
	v_exp_f32_e32 v58, v58
	v_exp_f32_e32 v59, v59
	v_add_f32_e32 v52, 1.0, v52
	v_add_f32_e32 v53, 1.0, v53
	v_add_f32_e32 v54, 1.0, v54
	v_add_f32_e32 v55, 1.0, v55
	v_add_f32_e32 v56, 1.0, v56
	v_add_f32_e32 v57, 1.0, v57
	v_add_f32_e32 v58, 1.0, v58
	v_add_f32_e32 v59, 1.0, v59
	v_rcp_f32_e32 v52, v52
	v_rcp_f32_e32 v53, v53
	v_rcp_f32_e32 v54, v54
	v_rcp_f32_e32 v55, v55
	v_rcp_f32_e32 v56, v56
	v_rcp_f32_e32 v57, v57
	v_rcp_f32_e32 v58, v58
	v_rcp_f32_e32 v59, v59
	v_pk_mul_f32 v[46:47], v[46:47], v[52:53]
	v_pk_mul_f32 v[48:49], v[48:49], v[54:55]
	v_pk_mul_f32 v[42:43], v[42:43], v[56:57]
	v_pk_mul_f32 v[44:45], v[44:45], v[58:59]
	v_pk_mul_f32 v[38:39], v[38:39], v[46:47]
	v_pk_mul_f32 v[40:41], v[40:41], v[48:49]
	v_pk_mul_f32 v[42:43], v[34:35], v[42:43]
	v_pk_mul_f32 v[44:45], v[36:37], v[44:45]
	v_cvt_pk_bf16_f32 v34, v38, v39
	v_cvt_pk_bf16_f32 v35, v40, v41
	v_cvt_pk_bf16_f32 v36, v42, v43
	v_cvt_pk_bf16_f32 v37, v44, v45
	global_store_dwordx4 v[50:51], v[34:37], off
	s_nop 0
	s_nop 0
	v_add_u32_e32 v35, 0xa0, v163
	s_waitcnt vmcnt(7)
	v_mov_b32_e32 v34, v217
	v_fmamk_f32 v34, v34, 0x3a800000, v161
	v_mul_f32_e32 v36, 0x4b800000, v34
	v_cmp_gt_f32_e32 vcc, s58, v34
	s_nop 1
	v_cndmask_b32_e32 v34, v34, v36, vcc
	v_rsq_f32_e32 v36, v34
	v_mad_i64_i32 v[34:35], s[4:5], v35, s59, v[138:139]
	v_lshl_add_u64 v[34:35], v[34:35], 0, v[140:141]
	v_mul_f32_e32 v37, 0x45800000, v36
	v_cndmask_b32_e32 v36, v36, v37, vcc
	v_pk_mul_f32 v[30:31], v[30:31], v[36:37] op_sel_hi:[1,0]
	v_pk_mul_f32 v[32:33], v[32:33], v[36:37] op_sel_hi:[1,0]
	v_pk_mul_f32 v[26:27], v[26:27], v[36:37] op_sel_hi:[1,0]
	v_pk_mul_f32 v[28:29], v[28:29], v[36:37] op_sel_hi:[1,0]
	v_pk_mul_f32 v[22:23], v[22:23], v[36:37] op_sel_hi:[1,0]
	v_pk_mul_f32 v[24:25], v[24:25], v[36:37] op_sel_hi:[1,0]
	v_pk_mul_f32 v[18:19], v[18:19], v[36:37] op_sel_hi:[1,0]
	v_pk_mul_f32 v[20:21], v[20:21], v[36:37] op_sel_hi:[1,0]
	v_mul_f32_e32 v36, 0xbfb8aa3b, v30
	v_mul_f32_e32 v37, 0xbfb8aa3b, v31
	v_mul_f32_e32 v38, 0xbfb8aa3b, v32
	v_mul_f32_e32 v39, 0xbfb8aa3b, v33
	v_mul_f32_e32 v40, 0xbfb8aa3b, v26
	v_mul_f32_e32 v41, 0xbfb8aa3b, v27
	v_mul_f32_e32 v42, 0xbfb8aa3b, v28
	v_mul_f32_e32 v43, 0xbfb8aa3b, v29
	v_exp_f32_e32 v36, v36
	v_exp_f32_e32 v37, v37
	v_exp_f32_e32 v38, v38
	v_exp_f32_e32 v39, v39
	v_exp_f32_e32 v40, v40
	v_exp_f32_e32 v41, v41
	v_exp_f32_e32 v42, v42
	v_exp_f32_e32 v43, v43
	v_add_f32_e32 v36, 1.0, v36
	v_add_f32_e32 v37, 1.0, v37
	v_add_f32_e32 v38, 1.0, v38
	v_add_f32_e32 v39, 1.0, v39
	v_add_f32_e32 v40, 1.0, v40
	v_add_f32_e32 v41, 1.0, v41
	v_add_f32_e32 v42, 1.0, v42
	v_add_f32_e32 v43, 1.0, v43
	v_rcp_f32_e32 v36, v36
	v_rcp_f32_e32 v37, v37
	v_rcp_f32_e32 v38, v38
	v_rcp_f32_e32 v39, v39
	v_rcp_f32_e32 v40, v40
	v_rcp_f32_e32 v41, v41
	v_rcp_f32_e32 v42, v42
	v_rcp_f32_e32 v43, v43
	v_pk_mul_f32 v[30:31], v[30:31], v[36:37]
	v_pk_mul_f32 v[32:33], v[32:33], v[38:39]
	v_pk_mul_f32 v[26:27], v[26:27], v[40:41]
	v_pk_mul_f32 v[28:29], v[28:29], v[42:43]
	v_pk_mul_f32 v[22:23], v[22:23], v[30:31]
	v_pk_mul_f32 v[24:25], v[24:25], v[32:33]
	v_pk_mul_f32 v[26:27], v[18:19], v[26:27]
	v_pk_mul_f32 v[28:29], v[20:21], v[28:29]
	v_cvt_pk_bf16_f32 v18, v22, v23
	v_cvt_pk_bf16_f32 v19, v24, v25
	v_cvt_pk_bf16_f32 v20, v26, v27
	v_cvt_pk_bf16_f32 v21, v28, v29
	global_store_dwordx4 v[34:35], v[18:21], off
	s_nop 0
	s_andn2_b64 vcc, exec, s[0:1]
	v_add_u32_e32 v19, 0xb0, v163
	s_mov_b64 s[0:1], -1
	s_waitcnt vmcnt(7)
	v_mov_b32_e32 v18, v218
	v_fmamk_f32 v18, v18, 0x3a800000, v161
	v_mul_f32_e32 v20, 0x4b800000, v18
	v_cmp_gt_f32_e64 s[4:5], s58, v18
	s_nop 1
	v_cndmask_b32_e64 v18, v18, v20, s[4:5]
	v_rsq_f32_e32 v20, v18
	v_mad_i64_i32 v[18:19], s[6:7], v19, s59, v[138:139]
	v_lshl_add_u64 v[18:19], v[18:19], 0, v[140:141]
	v_mul_f32_e32 v21, 0x45800000, v20
	v_cndmask_b32_e64 v20, v20, v21, s[4:5]
	v_pk_mul_f32 v[14:15], v[14:15], v[20:21] op_sel_hi:[1,0]
	v_pk_mul_f32 v[16:17], v[16:17], v[20:21] op_sel_hi:[1,0]
	v_pk_mul_f32 v[10:11], v[10:11], v[20:21] op_sel_hi:[1,0]
	v_pk_mul_f32 v[12:13], v[12:13], v[20:21] op_sel_hi:[1,0]
	v_pk_mul_f32 v[6:7], v[6:7], v[20:21] op_sel_hi:[1,0]
	v_pk_mul_f32 v[8:9], v[8:9], v[20:21] op_sel_hi:[1,0]
	v_pk_mul_f32 v[2:3], v[2:3], v[20:21] op_sel_hi:[1,0]
	v_pk_mul_f32 v[4:5], v[4:5], v[20:21] op_sel_hi:[1,0]
	v_mul_f32_e32 v20, 0xbfb8aa3b, v14
	v_mul_f32_e32 v21, 0xbfb8aa3b, v15
	v_mul_f32_e32 v22, 0xbfb8aa3b, v16
	v_mul_f32_e32 v23, 0xbfb8aa3b, v17
	v_mul_f32_e32 v24, 0xbfb8aa3b, v10
	v_mul_f32_e32 v25, 0xbfb8aa3b, v11
	v_mul_f32_e32 v26, 0xbfb8aa3b, v12
	v_mul_f32_e32 v27, 0xbfb8aa3b, v13
	v_exp_f32_e32 v20, v20
	v_exp_f32_e32 v21, v21
	v_exp_f32_e32 v22, v22
	v_exp_f32_e32 v23, v23
	v_exp_f32_e32 v24, v24
	v_exp_f32_e32 v25, v25
	v_exp_f32_e32 v26, v26
	v_exp_f32_e32 v27, v27
	v_add_f32_e32 v20, 1.0, v20
	v_add_f32_e32 v21, 1.0, v21
	v_add_f32_e32 v22, 1.0, v22
	v_add_f32_e32 v23, 1.0, v23
	v_add_f32_e32 v24, 1.0, v24
	v_add_f32_e32 v25, 1.0, v25
	v_add_f32_e32 v26, 1.0, v26
	v_add_f32_e32 v27, 1.0, v27
	v_rcp_f32_e32 v20, v20
	v_rcp_f32_e32 v21, v21
	v_rcp_f32_e32 v22, v22
	v_rcp_f32_e32 v23, v23
	v_rcp_f32_e32 v24, v24
	v_rcp_f32_e32 v25, v25
	v_rcp_f32_e32 v26, v26
	v_rcp_f32_e32 v27, v27
	v_pk_mul_f32 v[14:15], v[14:15], v[20:21]
	v_pk_mul_f32 v[16:17], v[16:17], v[22:23]
	v_pk_mul_f32 v[10:11], v[10:11], v[24:25]
	v_pk_mul_f32 v[12:13], v[12:13], v[26:27]
	v_pk_mul_f32 v[6:7], v[6:7], v[14:15]
	v_pk_mul_f32 v[8:9], v[8:9], v[16:17]
	v_pk_mul_f32 v[10:11], v[2:3], v[10:11]
	v_pk_mul_f32 v[12:13], v[4:5], v[12:13]
	v_cvt_pk_bf16_f32 v2, v6, v7
	v_cvt_pk_bf16_f32 v3, v8, v9
	v_cvt_pk_bf16_f32 v4, v10, v11
	v_cvt_pk_bf16_f32 v5, v12, v13
	global_store_dwordx4 v[18:19], v[2:5], off
	s_cbranch_vccnz .LBB0_1781
	s_andn2_b64 vcc, exec, s[8:9]
	s_cbranch_vccnz .LBB0_1780
	s_barrier
	s_branch .LBB0_1780
